# K-loops: s_setprio 1 moved before the pre-MFMA barrier, duplicate lgkmcnt(0) dropped (plus v12 transposed plain epilogue)
# speedup vs baseline: 1.0256x; 1.0100x over previous
; #define PG8_STAGE(bufoff, gbase, voff) do { _Pragma("unroll") for (int _i = 0; _i < 2; ++_i) \
;         __builtin_amdgcn_global_load_lds((const unsigned*)((const char*)(gbase) + (voff)[_i]), (LAS unsigned*)(lds + (bufoff) + ldsw + _i * 8192), 16, 0, 0); } while (0)
; #define PG8_LDA(dst, b, h) do { _Pragma("unroll") for (int m = 0; m < 4; ++m) _Pragma("unroll") for (int k = 0; k < 2; ++k) dst[m][k] = *(const LAS bf16x8*)(lds + PG8_SA(b, h) + aoff + m * 2048 + k * 1024); } while (0)
; #define PG8_LDB(dst, b, h) do { _Pragma("unroll") for (int n = 0; n < 2; ++n) _Pragma("unroll") for (int k = 0; k < 2; ++k) dst[n][k] = *(const LAS bf16x8*)(lds + PG8_SB(b, h) + boff + n * 2048 + k * 1024); } while (0)
; #define PG8_MMA(ai, bj, At, Bt) do { __builtin_amdgcn_s_setprio(1); _Pragma("unroll") for (int m = 0; m < 4; ++m) _Pragma("unroll") for (int n = 0; n < 2; ++n) _Pragma("unroll") for (int k = 0; k < 2; ++k) \
;         acc[ai][bj][m][n] = __builtin_amdgcn_mfma_f32_16x16x32_bf16(Bt[n][k], At[m][k], acc[ai][bj][m][n], 0, 0, 0); __builtin_amdgcn_s_setprio(0); } while (0)
; #define PG8_WAIT_L(n) asm volatile("s_waitcnt lgkmcnt(" #n ")" ::: "memory")
; #define PG8_BAR __builtin_amdgcn_s_barrier()
; #define PG8_SCHED __builtin_amdgcn_sched_barrier(0)
; template <class Epi>
; DI void gemm_phase(LAS unsigned char* lds, const Gemm g, const StaticOrder& S_, const Epi& E) {
;     ...
;         for (int t = tb; t < te; t += 2) {
;             const bool last = (t == nt - 2);
;             const bool hA = (t >= ksplit), hB = (t + 2 >= ksplit);
;             const char* a1 = (hA ? cA1 : cA0) + (size_t)(t + 1) * kstep;
;             const char* a2 = last ? nA0 : (hB ? cA1 : cA0) + (size_t)(t + 2) * kstep; const char* b2 = last ? nB0 : (hB ? cB1 : cB0) + (size_t)(t + 2) * kstep;
;             const char* a3 = a2 + kstep; const char* b3 = b2 + kstep;
;             PG8_LDB(B0, 0, 0); PG8_SCHED; PG8_LDA(At, 0, 0); PG8_STAGE(PG8_SA(1, 1), a1 + hstepA, voffA);
;             PG8_WAIT_L(8); PG8_BAR; PG8_WAIT_L(0); PG8_MMA(0, 0, At, B0); PG8_BAR; PG8_SCHED;
;             PG8_LDB(B1, 0, 1); PG8_STAGE(PG8_SB(0, 0), b2, voffB);
;             PG8_BAR; PG8_WAIT_L(0); PG8_MMA(0, 1, At, B1); PG8_BAR;
;             PG8_LDA(At, 0, 1); PG8_STAGE(PG8_SA(0, 0), a2, voffA);
;             PG8_BAR; PG8_WAIT_L(0); PG8_MMA(1, 0, At, B0); PG8_BAR; PG8_SCHED;
.LBB0_114:
	s_add_i32 s94, s56, 2
	s_cmp_gt_u32 s94, 29
	s_cselect_b64 s[58:59], -1, 0
	s_and_b64 vcc, s[58:59], exec
	s_cselect_b32 s58, s18, s6
	s_cselect_b32 s57, s51, s7
	s_cselect_b32 s59, s91, s49
	s_cselect_b32 s95, s53, s48
	s_add_u32 s58, s58, s54
	s_addc_u32 s57, s57, s55
	s_add_u32 s58, s58, 0xfff80080
	s_addc_u32 s57, s57, -1
	ds_read_b128 v[132:135], v210
	ds_read_b128 v[136:139], v210 offset:1024
	ds_read_b128 v[140:143], v210 offset:2048
	ds_read_b128 v[144:147], v210 offset:3072
	s_add_u32 s95, s95, s54
	s_addc_u32 s59, s59, s55
	s_add_u32 s95, s95, 0xfff80080
	s_addc_u32 s96, s59, -1
	s_cmp_eq_u32 s56, 28
	s_cselect_b32 s56, s93, s95
	s_cselect_b32 s59, s43, s57
	s_cselect_b32 s58, s92, s58
	s_cselect_b32 s57, s41, s96
	v_lshl_add_u64 v[214:215], v[128:129], 0, s[54:55]
	s_add_i32 m0, s69, 0xc000
	ds_read_b128 v[148:151], v211
	ds_read_b128 v[152:155], v211 offset:1024
	ds_read_b128 v[156:159], v211 offset:2048
	ds_read_b128 v[160:163], v211 offset:3072
	ds_read_b128 v[164:167], v211 offset:4096
	ds_read_b128 v[168:171], v211 offset:5120
	ds_read_b128 v[172:175], v211 offset:6144
	ds_read_b128 v[198:201], v211 offset:7168
	global_load_lds_dwordx4 v[214:215], off
	v_lshl_add_u64 v[214:215], v[130:131], 0, s[54:55]
	s_add_i32 m0, s69, 0xe000
	s_nop 0
	global_load_lds_dwordx4 v[214:215], off
	s_waitcnt lgkmcnt(8)
	s_setprio 1
	s_barrier
	s_waitcnt lgkmcnt(0)
	v_mfma_f32_16x16x32_bf16 v[124:127], v[132:135], v[148:151], v[124:127]
	v_mfma_f32_16x16x32_bf16 v[120:123], v[140:143], v[148:151], v[120:123]
	v_mfma_f32_16x16x32_bf16 v[108:111], v[132:135], v[156:159], v[108:111]
	v_mfma_f32_16x16x32_bf16 v[104:107], v[140:143], v[156:159], v[104:107]
	v_mfma_f32_16x16x32_bf16 v[92:95], v[132:135], v[164:167], v[92:95]
	v_mfma_f32_16x16x32_bf16 v[88:91], v[140:143], v[164:167], v[88:91]
	v_mfma_f32_16x16x32_bf16 v[76:79], v[132:135], v[172:175], v[76:79]
	v_mfma_f32_16x16x32_bf16 v[72:75], v[140:143], v[172:175], v[72:75]
	v_mfma_f32_16x16x32_bf16 v[124:127], v[136:139], v[152:155], v[124:127]
	v_mfma_f32_16x16x32_bf16 v[120:123], v[144:147], v[152:155], v[120:123]
	v_mfma_f32_16x16x32_bf16 v[108:111], v[136:139], v[160:163], v[108:111]
	v_mfma_f32_16x16x32_bf16 v[104:107], v[144:147], v[160:163], v[104:107]
	v_mfma_f32_16x16x32_bf16 v[92:95], v[136:139], v[168:171], v[92:95]
	v_mfma_f32_16x16x32_bf16 v[88:91], v[144:147], v[168:171], v[88:91]
	v_mfma_f32_16x16x32_bf16 v[76:79], v[136:139], v[198:201], v[76:79]
	v_mfma_f32_16x16x32_bf16 v[72:75], v[144:147], v[198:201], v[72:75]
	s_setprio 0
	s_barrier
	s_add_i32 s95, s82, s64
	v_lshl_add_u64 v[230:231], s[56:57], 0, v[180:181]
	s_mov_b32 m0, s95
	ds_read_b128 v[214:217], v212
	ds_read_b128 v[218:221], v212 offset:1024
	ds_read_b128 v[222:225], v212 offset:2048
	ds_read_b128 v[226:229], v212 offset:3072
	global_load_lds_dwordx4 v[230:231], off
	v_lshl_add_u64 v[232:233], s[56:57], 0, v[176:177]
	s_add_i32 m0, s95, 0x2000
	s_nop 0
	global_load_lds_dwordx4 v[232:233], off
	s_setprio 1
	s_barrier
	s_waitcnt lgkmcnt(0)
	v_mfma_f32_16x16x32_bf16 v[116:119], v[214:217], v[148:151], v[116:119]
	v_mfma_f32_16x16x32_bf16 v[112:115], v[222:225], v[148:151], v[112:115]
	v_mfma_f32_16x16x32_bf16 v[100:103], v[214:217], v[156:159], v[100:103]
	v_mfma_f32_16x16x32_bf16 v[96:99], v[222:225], v[156:159], v[96:99]
	v_mfma_f32_16x16x32_bf16 v[84:87], v[214:217], v[164:167], v[84:87]
	v_mfma_f32_16x16x32_bf16 v[80:83], v[222:225], v[164:167], v[80:83]
	v_mfma_f32_16x16x32_bf16 v[68:71], v[214:217], v[172:175], v[68:71]
	v_mfma_f32_16x16x32_bf16 v[64:67], v[222:225], v[172:175], v[64:67]
	v_mfma_f32_16x16x32_bf16 v[116:119], v[218:221], v[152:155], v[116:119]
	v_mfma_f32_16x16x32_bf16 v[112:115], v[226:229], v[152:155], v[112:115]
	v_mfma_f32_16x16x32_bf16 v[100:103], v[218:221], v[160:163], v[100:103]
	v_mfma_f32_16x16x32_bf16 v[96:99], v[226:229], v[160:163], v[96:99]
	v_mfma_f32_16x16x32_bf16 v[84:87], v[218:221], v[168:171], v[84:87]
	v_mfma_f32_16x16x32_bf16 v[80:83], v[226:229], v[168:171], v[80:83]
	v_mfma_f32_16x16x32_bf16 v[68:71], v[218:221], v[198:201], v[68:71]
	v_mfma_f32_16x16x32_bf16 v[64:67], v[226:229], v[198:201], v[64:67]
	s_setprio 0
	s_mov_b32 m0, s69
	v_lshl_add_u64 v[234:235], s[58:59], 0, v[182:183]
	s_barrier
	ds_read_b128 v[148:151], v211 offset:16384
	ds_read_b128 v[152:155], v211 offset:17408
	ds_read_b128 v[156:159], v211 offset:18432
	ds_read_b128 v[160:163], v211 offset:19456
	ds_read_b128 v[164:167], v211 offset:20480
	ds_read_b128 v[168:171], v211 offset:21504
	ds_read_b128 v[172:175], v211 offset:22528
	ds_read_b128 v[198:201], v211 offset:23552
	global_load_lds_dwordx4 v[234:235], off
	v_lshl_add_u64 v[236:237], s[58:59], 0, v[178:179]
	s_mov_b32 m0, s70
	s_nop 0
	global_load_lds_dwordx4 v[236:237], off
	s_setprio 1
	s_barrier
	s_waitcnt lgkmcnt(0)
	v_mfma_f32_16x16x32_bf16 v[60:63], v[132:135], v[148:151], v[60:63]
	v_mfma_f32_16x16x32_bf16 v[56:59], v[140:143], v[148:151], v[56:59]
	v_mfma_f32_16x16x32_bf16 v[44:47], v[132:135], v[156:159], v[44:47]
	v_mfma_f32_16x16x32_bf16 v[40:43], v[140:143], v[156:159], v[40:43]
	v_mfma_f32_16x16x32_bf16 v[28:31], v[132:135], v[164:167], v[28:31]
	v_mfma_f32_16x16x32_bf16 v[24:27], v[140:143], v[164:167], v[24:27]
	v_mfma_f32_16x16x32_bf16 v[12:15], v[132:135], v[172:175], v[12:15]
	v_mfma_f32_16x16x32_bf16 v[8:11], v[140:143], v[172:175], v[8:11]
	v_mfma_f32_16x16x32_bf16 v[60:63], v[136:139], v[152:155], v[60:63]
	v_mfma_f32_16x16x32_bf16 v[56:59], v[144:147], v[152:155], v[56:59]
	v_mfma_f32_16x16x32_bf16 v[44:47], v[136:139], v[160:163], v[44:47]
	v_mfma_f32_16x16x32_bf16 v[40:43], v[144:147], v[160:163], v[40:43]
	v_mfma_f32_16x16x32_bf16 v[28:31], v[136:139], v[168:171], v[28:31]
	v_mfma_f32_16x16x32_bf16 v[24:27], v[144:147], v[168:171], v[24:27]
	v_mfma_f32_16x16x32_bf16 v[12:15], v[136:139], v[198:201], v[12:15]
	v_mfma_f32_16x16x32_bf16 v[8:11], v[144:147], v[198:201], v[8:11]
	s_setprio 0
	s_barrier
; #define PG8_STAGE(bufoff, gbase, voff) do { _Pragma("unroll") for (int _i = 0; _i < 2; ++_i) \
;         __builtin_amdgcn_global_load_lds((const unsigned*)((const char*)(gbase) + (voff)[_i]), (LAS unsigned*)(lds + (bufoff) + ldsw + _i * 8192), 16, 0, 0); } while (0)
; #define PG8_LDA(dst, b, h) do { _Pragma("unroll") for (int m = 0; m < 4; ++m) _Pragma("unroll") for (int k = 0; k < 2; ++k) dst[m][k] = *(const LAS bf16x8*)(lds + PG8_SA(b, h) + aoff + m * 2048 + k * 1024); } while (0)
; #define PG8_LDB(dst, b, h) do { _Pragma("unroll") for (int n = 0; n < 2; ++n) _Pragma("unroll") for (int k = 0; k < 2; ++k) dst[n][k] = *(const LAS bf16x8*)(lds + PG8_SB(b, h) + boff + n * 2048 + k * 1024); } while (0)
; #define PG8_MMA(ai, bj, At, Bt) do { __builtin_amdgcn_s_setprio(1); _Pragma("unroll") for (int m = 0; m < 4; ++m) _Pragma("unroll") for (int n = 0; n < 2; ++n) _Pragma("unroll") for (int k = 0; k < 2; ++k) \
;         acc[ai][bj][m][n] = __builtin_amdgcn_mfma_f32_16x16x32_bf16(Bt[n][k], At[m][k], acc[ai][bj][m][n], 0, 0, 0); __builtin_amdgcn_s_setprio(0); } while (0)
; #define PG8_WAIT_V(n) asm volatile("s_waitcnt vmcnt(" #n ")" ::: "memory")
; #define PG8_WAIT_L(n) asm volatile("s_waitcnt lgkmcnt(" #n ")" ::: "memory")
; #define PG8_BAR __builtin_amdgcn_s_barrier()
; #define PG8_SCHED __builtin_amdgcn_sched_barrier(0)
; template <class Epi>
; DI void gemm_phase(LAS unsigned char* lds, const Gemm g, const StaticOrder& S_, const Epi& E) {
;     ...
;             PG8_STAGE(PG8_SB(0, 1), b2 + hstepB, voffB);
;             PG8_WAIT_V(6); PG8_BAR; PG8_MMA(1, 1, At, B1); PG8_BAR;
;             PG8_LDB(B0, 1, 0); PG8_SCHED; PG8_LDA(At, 1, 0); PG8_STAGE(PG8_SA(0, 1), a2 + hstepA, voffA);
;             PG8_WAIT_L(8); PG8_BAR; PG8_WAIT_L(0); PG8_MMA(0, 0, At, B0); PG8_BAR; PG8_SCHED;
;             PG8_LDB(B1, 1, 1); PG8_STAGE(PG8_SB(1, 0), b3, voffB);
	s_add_u32 s96, s56, 0x80000
	s_addc_u32 s97, s57, 0
	s_add_i32 s95, s83, s64
	v_lshl_add_u64 v[132:133], s[96:97], 0, v[180:181]
	s_mov_b32 m0, s95
	s_nop 0
	global_load_lds_dwordx4 v[132:133], off
	v_lshl_add_u64 v[132:133], s[96:97], 0, v[176:177]
	s_add_i32 m0, s95, 0x2000
	s_nop 0
	global_load_lds_dwordx4 v[132:133], off
	s_waitcnt vmcnt(6)
	s_setprio 1
	s_barrier
	v_mfma_f32_16x16x32_bf16 v[52:55], v[214:217], v[148:151], v[52:55]
	v_mfma_f32_16x16x32_bf16 v[48:51], v[222:225], v[148:151], v[48:51]
	v_mfma_f32_16x16x32_bf16 v[36:39], v[214:217], v[156:159], v[36:39]
	v_mfma_f32_16x16x32_bf16 v[32:35], v[222:225], v[156:159], v[32:35]
	v_mfma_f32_16x16x32_bf16 v[20:23], v[214:217], v[164:167], v[20:23]
	v_mfma_f32_16x16x32_bf16 v[16:19], v[222:225], v[164:167], v[16:19]
	v_mfma_f32_16x16x32_bf16 v[4:7], v[214:217], v[172:175], v[4:7]
	v_mfma_f32_16x16x32_bf16 v[0:3], v[222:225], v[172:175], v[0:3]
	v_mfma_f32_16x16x32_bf16 v[52:55], v[218:221], v[152:155], v[52:55]
	v_mfma_f32_16x16x32_bf16 v[48:51], v[226:229], v[152:155], v[48:51]
	v_mfma_f32_16x16x32_bf16 v[36:39], v[218:221], v[160:163], v[36:39]
	v_mfma_f32_16x16x32_bf16 v[32:35], v[226:229], v[160:163], v[32:35]
	v_mfma_f32_16x16x32_bf16 v[20:23], v[218:221], v[168:171], v[20:23]
	v_mfma_f32_16x16x32_bf16 v[16:19], v[226:229], v[168:171], v[16:19]
	v_mfma_f32_16x16x32_bf16 v[4:7], v[218:221], v[198:201], v[4:7]
	v_mfma_f32_16x16x32_bf16 v[0:3], v[226:229], v[198:201], v[0:3]
	s_setprio 0
	s_add_i32 s95, 0, 0x18000
	v_add_u32_e32 v144, s95, v208
	s_barrier
	ds_read_b128 v[132:135], v144
	ds_read_b128 v[136:139], v144 offset:1024
	ds_read_b128 v[140:143], v144 offset:2048
	ds_read_b128 v[144:147], v144 offset:3072
	s_add_u32 s58, s58, 0x80000
	s_addc_u32 s59, s59, 0
	s_mov_b32 m0, s71
	v_lshl_add_u64 v[214:215], s[58:59], 0, v[182:183]
	ds_read_b128 v[148:151], v211 offset:32768
	ds_read_b128 v[152:155], v211 offset:33792
	ds_read_b128 v[156:159], v211 offset:34816
	ds_read_b128 v[160:163], v211 offset:35840
	ds_read_b128 v[164:167], v211 offset:36864
	ds_read_b128 v[168:171], v211 offset:37888
	ds_read_b128 v[172:175], v211 offset:38912
	ds_read_b128 v[198:201], v211 offset:39936
	global_load_lds_dwordx4 v[214:215], off
	v_lshl_add_u64 v[214:215], s[58:59], 0, v[178:179]
	s_mov_b32 m0, s72
	s_nop 0
	global_load_lds_dwordx4 v[214:215], off
	s_waitcnt lgkmcnt(8)
	s_setprio 1
	s_barrier
	s_waitcnt lgkmcnt(0)
	v_mfma_f32_16x16x32_bf16 v[124:127], v[132:135], v[148:151], v[124:127]
	v_mfma_f32_16x16x32_bf16 v[120:123], v[140:143], v[148:151], v[120:123]
	v_mfma_f32_16x16x32_bf16 v[108:111], v[132:135], v[156:159], v[108:111]
	v_mfma_f32_16x16x32_bf16 v[104:107], v[140:143], v[156:159], v[104:107]
	v_mfma_f32_16x16x32_bf16 v[92:95], v[132:135], v[164:167], v[92:95]
	v_mfma_f32_16x16x32_bf16 v[88:91], v[140:143], v[164:167], v[88:91]
	v_mfma_f32_16x16x32_bf16 v[76:79], v[132:135], v[172:175], v[76:79]
	v_mfma_f32_16x16x32_bf16 v[72:75], v[140:143], v[172:175], v[72:75]
	v_mfma_f32_16x16x32_bf16 v[124:127], v[136:139], v[152:155], v[124:127]
	v_mfma_f32_16x16x32_bf16 v[120:123], v[144:147], v[152:155], v[120:123]
	v_mfma_f32_16x16x32_bf16 v[108:111], v[136:139], v[160:163], v[108:111]
	v_mfma_f32_16x16x32_bf16 v[104:107], v[144:147], v[160:163], v[104:107]
	v_mfma_f32_16x16x32_bf16 v[92:95], v[136:139], v[168:171], v[92:95]
	v_mfma_f32_16x16x32_bf16 v[88:91], v[144:147], v[168:171], v[88:91]
	v_mfma_f32_16x16x32_bf16 v[76:79], v[136:139], v[198:201], v[76:79]
	v_mfma_f32_16x16x32_bf16 v[72:75], v[144:147], v[198:201], v[72:75]
	s_setprio 0
	s_barrier
	s_add_i32 s58, 0, 0x1c000
	s_add_i32 s59, s95, s64
	v_add_u32_e32 v184, s58, v208
	v_lshl_add_u64 v[230:231], v[230:231], 0, s[22:23]
	s_mov_b32 m0, s59
	ds_read_b128 v[214:217], v184
	ds_read_b128 v[218:221], v184 offset:1024
	ds_read_b128 v[222:225], v184 offset:2048
	ds_read_b128 v[226:229], v184 offset:3072
	global_load_lds_dwordx4 v[230:231], off
	v_lshl_add_u64 v[230:231], v[232:233], 0, s[22:23]
	s_add_i32 m0, s59, 0x2000
	s_nop 0
	global_load_lds_dwordx4 v[230:231], off
	s_setprio 1
	s_barrier
; #define PG8_STAGE(bufoff, gbase, voff) do { _Pragma("unroll") for (int _i = 0; _i < 2; ++_i) \
;         __builtin_amdgcn_global_load_lds((const unsigned*)((const char*)(gbase) + (voff)[_i]), (LAS unsigned*)(lds + (bufoff) + ldsw + _i * 8192), 16, 0, 0); } while (0)
; #define PG8_LDA(dst, b, h) do { _Pragma("unroll") for (int m = 0; m < 4; ++m) _Pragma("unroll") for (int k = 0; k < 2; ++k) dst[m][k] = *(const LAS bf16x8*)(lds + PG8_SA(b, h) + aoff + m * 2048 + k * 1024); } while (0)
; #define PG8_LDB(dst, b, h) do { _Pragma("unroll") for (int n = 0; n < 2; ++n) _Pragma("unroll") for (int k = 0; k < 2; ++k) dst[n][k] = *(const LAS bf16x8*)(lds + PG8_SB(b, h) + boff + n * 2048 + k * 1024); } while (0)
; #define PG8_MMA(ai, bj, At, Bt) do { __builtin_amdgcn_s_setprio(1); _Pragma("unroll") for (int m = 0; m < 4; ++m) _Pragma("unroll") for (int n = 0; n < 2; ++n) _Pragma("unroll") for (int k = 0; k < 2; ++k) \
;         acc[ai][bj][m][n] = __builtin_amdgcn_mfma_f32_16x16x32_bf16(Bt[n][k], At[m][k], acc[ai][bj][m][n], 0, 0, 0); __builtin_amdgcn_s_setprio(0); } while (0)
; #define PG8_WAIT_V(n) asm volatile("s_waitcnt vmcnt(" #n ")" ::: "memory")
; template <class Epi>
; DI void gemm_phase(LAS unsigned char* lds, const Gemm g, const StaticOrder& S_, const Epi& E) {
;     ...
;             PG8_LDB(B1, 1, 1); PG8_STAGE(PG8_SB(1, 0), b3, voffB);
;             PG8_BAR; PG8_WAIT_L(0); PG8_MMA(0, 1, At, B1); PG8_BAR;
;             PG8_LDA(At, 1, 1); PG8_STAGE(PG8_SA(1, 0), a3, voffA);
;             PG8_BAR; PG8_WAIT_L(0); PG8_MMA(1, 0, At, B0); PG8_BAR; PG8_SCHED;
;             PG8_STAGE(PG8_SB(1, 1), b3 + hstepB, voffB);
;             PG8_WAIT_V(6); PG8_BAR; PG8_MMA(1, 1, At, B1); PG8_BAR;
;     DI void operator()(const f32x4 (&acc)[2][2][4][2], const pg8::Unit& u, int wr, int wc, int fr, int fq) const {
;         const int pn = u.pn; bf16_t* base; int ld, colt;
;         if (pn < 8) { base = (bf16_t*)(ws + WS_ZU) + (size_t)pn * S * 256; ld = 256; colt = 0; }
;         else if (pn < 16) { base = (bf16_t*)(ws + WS_ZG); ld = 2048; colt = (pn - 8) * 256; }
;         else if (pn < 28) { base = (bf16_t*)(ws + WS_ZQKV); ld = 3072; colt = (pn - 16) * 256; }
;         else if (pn < 36) { base = (bf16_t*)(ws + WS_ZGA); ld = 2048; colt = (pn - 28) * 256; }
;         else { base = (bf16_t*)(ws + WS_ZM) + (size_t)(pn - 36) * S * 256; ld = 256; colt = 0; }
	s_waitcnt lgkmcnt(0)
	v_mfma_f32_16x16x32_bf16 v[116:119], v[214:217], v[148:151], v[116:119]
	v_mfma_f32_16x16x32_bf16 v[112:115], v[222:225], v[148:151], v[112:115]
	v_mfma_f32_16x16x32_bf16 v[100:103], v[214:217], v[156:159], v[100:103]
	v_mfma_f32_16x16x32_bf16 v[96:99], v[222:225], v[156:159], v[96:99]
	v_mfma_f32_16x16x32_bf16 v[84:87], v[214:217], v[164:167], v[84:87]
	v_mfma_f32_16x16x32_bf16 v[80:83], v[222:225], v[164:167], v[80:83]
	v_mfma_f32_16x16x32_bf16 v[68:71], v[214:217], v[172:175], v[68:71]
	v_mfma_f32_16x16x32_bf16 v[64:67], v[222:225], v[172:175], v[64:67]
	v_mfma_f32_16x16x32_bf16 v[116:119], v[218:221], v[152:155], v[116:119]
	v_mfma_f32_16x16x32_bf16 v[112:115], v[226:229], v[152:155], v[112:115]
	v_mfma_f32_16x16x32_bf16 v[100:103], v[218:221], v[160:163], v[100:103]
	v_mfma_f32_16x16x32_bf16 v[96:99], v[226:229], v[160:163], v[96:99]
	v_mfma_f32_16x16x32_bf16 v[84:87], v[218:221], v[168:171], v[84:87]
	v_mfma_f32_16x16x32_bf16 v[80:83], v[226:229], v[168:171], v[80:83]
	v_mfma_f32_16x16x32_bf16 v[68:71], v[218:221], v[198:201], v[68:71]
	v_mfma_f32_16x16x32_bf16 v[64:67], v[226:229], v[198:201], v[64:67]
	s_setprio 0
	s_mov_b32 m0, s74
	v_lshl_add_u64 v[230:231], v[234:235], 0, s[22:23]
	s_barrier
	ds_read_b128 v[148:151], v211 offset:49152
	ds_read_b128 v[152:155], v211 offset:50176
	ds_read_b128 v[156:159], v211 offset:51200
	ds_read_b128 v[160:163], v211 offset:52224
	ds_read_b128 v[164:167], v211 offset:53248
	ds_read_b128 v[168:171], v211 offset:54272
	ds_read_b128 v[172:175], v211 offset:55296
	ds_read_b128 v[198:201], v211 offset:56320
	global_load_lds_dwordx4 v[230:231], off
	v_lshl_add_u64 v[230:231], v[236:237], 0, s[22:23]
	s_mov_b32 m0, s75
	s_nop 0
	global_load_lds_dwordx4 v[230:231], off
	s_setprio 1
	s_barrier
	s_waitcnt lgkmcnt(0)
	v_mfma_f32_16x16x32_bf16 v[60:63], v[132:135], v[148:151], v[60:63]
	v_mfma_f32_16x16x32_bf16 v[56:59], v[140:143], v[148:151], v[56:59]
	v_mfma_f32_16x16x32_bf16 v[44:47], v[132:135], v[156:159], v[44:47]
	v_mfma_f32_16x16x32_bf16 v[40:43], v[140:143], v[156:159], v[40:43]
	v_mfma_f32_16x16x32_bf16 v[28:31], v[132:135], v[164:167], v[28:31]
	v_mfma_f32_16x16x32_bf16 v[24:27], v[140:143], v[164:167], v[24:27]
	v_mfma_f32_16x16x32_bf16 v[12:15], v[132:135], v[172:175], v[12:15]
	v_mfma_f32_16x16x32_bf16 v[8:11], v[140:143], v[172:175], v[8:11]
	v_mfma_f32_16x16x32_bf16 v[60:63], v[136:139], v[152:155], v[60:63]
	v_mfma_f32_16x16x32_bf16 v[56:59], v[144:147], v[152:155], v[56:59]
	v_mfma_f32_16x16x32_bf16 v[44:47], v[136:139], v[160:163], v[44:47]
	v_mfma_f32_16x16x32_bf16 v[40:43], v[144:147], v[160:163], v[40:43]
	v_mfma_f32_16x16x32_bf16 v[28:31], v[136:139], v[168:171], v[28:31]
	v_mfma_f32_16x16x32_bf16 v[24:27], v[144:147], v[168:171], v[24:27]
	v_mfma_f32_16x16x32_bf16 v[12:15], v[136:139], v[198:201], v[12:15]
	v_mfma_f32_16x16x32_bf16 v[8:11], v[144:147], v[198:201], v[8:11]
	s_setprio 0
	s_barrier
	s_add_u32 s56, s56, 0x80080
	s_addc_u32 s57, s57, 0
	s_add_i32 s58, s58, s64
	v_lshl_add_u64 v[132:133], s[56:57], 0, v[180:181]
	s_mov_b32 m0, s58
	s_nop 0
	global_load_lds_dwordx4 v[132:133], off
	v_lshl_add_u64 v[132:133], s[56:57], 0, v[176:177]
	s_add_i32 m0, s58, 0x2000
	s_nop 0
	global_load_lds_dwordx4 v[132:133], off
	s_waitcnt vmcnt(6)
	s_setprio 1
	s_barrier
	v_mfma_f32_16x16x32_bf16 v[52:55], v[214:217], v[148:151], v[52:55]
	v_mfma_f32_16x16x32_bf16 v[48:51], v[222:225], v[148:151], v[48:51]
	v_mfma_f32_16x16x32_bf16 v[36:39], v[214:217], v[156:159], v[36:39]
	v_mfma_f32_16x16x32_bf16 v[32:35], v[222:225], v[156:159], v[32:35]
	v_mfma_f32_16x16x32_bf16 v[20:23], v[214:217], v[164:167], v[20:23]
	v_mfma_f32_16x16x32_bf16 v[16:19], v[222:225], v[164:167], v[16:19]
	v_mfma_f32_16x16x32_bf16 v[4:7], v[214:217], v[172:175], v[4:7]
	v_mfma_f32_16x16x32_bf16 v[0:3], v[222:225], v[172:175], v[0:3]
	v_mfma_f32_16x16x32_bf16 v[52:55], v[218:221], v[152:155], v[52:55]
	v_mfma_f32_16x16x32_bf16 v[48:51], v[226:229], v[152:155], v[48:51]
	v_mfma_f32_16x16x32_bf16 v[36:39], v[218:221], v[160:163], v[36:39]
	v_mfma_f32_16x16x32_bf16 v[32:35], v[226:229], v[160:163], v[32:35]
	v_mfma_f32_16x16x32_bf16 v[20:23], v[218:221], v[168:171], v[20:23]
	v_mfma_f32_16x16x32_bf16 v[16:19], v[226:229], v[168:171], v[16:19]
	v_mfma_f32_16x16x32_bf16 v[4:7], v[218:221], v[198:201], v[4:7]
	v_mfma_f32_16x16x32_bf16 v[0:3], v[226:229], v[198:201], v[0:3]
	s_setprio 0
	s_add_u32 s54, s54, 0x100
	s_addc_u32 s55, s55, 0
	s_mov_b32 s56, s94
	s_barrier
	s_cbranch_vccz .LBB0_114
	s_cmp_gt_i32 s50, 7
	s_mov_b64 s[54:55], -1
	s_cbranch_scc0 .LBB0_128
	s_cmp_gt_u32 s50, 15
	s_cbranch_scc0 .LBB0_125
	s_cmp_gt_u32 s50, 27
	s_cbranch_scc0 .LBB0_122
	s_cmp_gt_u32 s50, 35
	s_mov_b64 s[48:49], -1
	s_cbranch_scc0 .LBB0_120
	s_sub_i32 s18, s50, 36
	s_lshl_b64 s[6:7], s[18:19], 23
	s_add_u32 s6, s78, s6
	s_addc_u32 s7, s79, s7
	s_mov_b64 s[48:49], 0

; #define PG8_STAGE(bufoff, gbase, voff) do { _Pragma("unroll") for (int _i = 0; _i < 2; ++_i) \
;         __builtin_amdgcn_global_load_lds((const unsigned*)((const char*)(gbase) + (voff)[_i]), (LAS unsigned*)(lds + (bufoff) + ldsw + _i * 8192), 16, 0, 0); } while (0)
; #define PG8_LDA(dst, b, h) do { _Pragma("unroll") for (int m = 0; m < 4; ++m) _Pragma("unroll") for (int k = 0; k < 2; ++k) dst[m][k] = *(const LAS bf16x8*)(lds + PG8_SA(b, h) + aoff + m * 2048 + k * 1024); } while (0)
; #define PG8_LDB(dst, b, h) do { _Pragma("unroll") for (int n = 0; n < 2; ++n) _Pragma("unroll") for (int k = 0; k < 2; ++k) dst[n][k] = *(const LAS bf16x8*)(lds + PG8_SB(b, h) + boff + n * 2048 + k * 1024); } while (0)
; #define PG8_MMA(ai, bj, At, Bt) do { __builtin_amdgcn_s_setprio(1); _Pragma("unroll") for (int m = 0; m < 4; ++m) _Pragma("unroll") for (int n = 0; n < 2; ++n) _Pragma("unroll") for (int k = 0; k < 2; ++k) \
;         acc[ai][bj][m][n] = __builtin_amdgcn_mfma_f32_16x16x32_bf16(Bt[n][k], At[m][k], acc[ai][bj][m][n], 0, 0, 0); __builtin_amdgcn_s_setprio(0); } while (0)
; #define PG8_WAIT_L(n) asm volatile("s_waitcnt lgkmcnt(" #n ")" ::: "memory")
; #define PG8_BAR __builtin_amdgcn_s_barrier()
; #define PG8_SCHED __builtin_amdgcn_sched_barrier(0)
; template <class Epi>
; DI void gemm_phase(LAS unsigned char* lds, const Gemm g, const StaticOrder& S_, const Epi& E) {
;     ...
;         for (int t = tb; t < te; t += 2) {
;             const bool last = (t == nt - 2);
;             const bool hA = (t >= ksplit), hB = (t + 2 >= ksplit);
;             const char* a1 = (hA ? cA1 : cA0) + (size_t)(t + 1) * kstep;
;             const char* a2 = last ? nA0 : (hB ? cA1 : cA0) + (size_t)(t + 2) * kstep; const char* b2 = last ? nB0 : (hB ? cB1 : cB0) + (size_t)(t + 2) * kstep;
;             const char* a3 = a2 + kstep; const char* b3 = b2 + kstep;
;             PG8_LDB(B0, 0, 0); PG8_SCHED; PG8_LDA(At, 0, 0); PG8_STAGE(PG8_SA(1, 1), a1 + hstepA, voffA);
;             PG8_WAIT_L(8); PG8_BAR; PG8_WAIT_L(0); PG8_MMA(0, 0, At, B0); PG8_BAR; PG8_SCHED;
;             PG8_LDB(B1, 0, 1); PG8_STAGE(PG8_SB(0, 0), b2, voffB);
;             PG8_BAR; PG8_WAIT_L(0); PG8_MMA(0, 1, At, B1); PG8_BAR;
;             PG8_LDA(At, 0, 1); PG8_STAGE(PG8_SA(0, 0), a2, voffA);
;             PG8_BAR; PG8_WAIT_L(0); PG8_MMA(1, 0, At, B0); PG8_BAR; PG8_SCHED;
.LBB0_450:
	s_add_i32 s82, s14, 2
	s_cmp_gt_u32 s14, 29
	s_cselect_b32 s49, s74, s38
	s_cselect_b32 s48, s75, s39
	s_cselect_b32 s50, s77, s41
	s_cselect_b32 s51, s76, s40
	s_add_u32 s49, s49, s46
	s_addc_u32 s48, s48, s47
	s_add_u32 s49, s49, 0x100
	v_add_u32_e32 v0, s70, v205
	s_addc_u32 s48, s48, 0
	ds_read_b128 v[148:151], v0
	ds_read_b128 v[152:155], v0 offset:1024
	ds_read_b128 v[156:159], v0 offset:2048
	ds_read_b128 v[160:163], v0 offset:3072
	s_add_u32 s51, s51, s46
	s_addc_u32 s50, s50, s47
	s_add_u32 s83, s51, 0x100
	s_addc_u32 s86, s50, 0
	s_cmp_gt_u32 s14, 31
	s_cselect_b32 s84, s74, s38
	s_cselect_b32 s85, s75, s39
	s_cmpk_eq_i32 s46, 0x1f00
	s_cselect_b32 s51, s23, s48
	s_cselect_b32 s50, s78, s49
	s_cselect_b32 s49, s79, s86
	s_cselect_b32 s48, s80, s83
	v_lshl_add_u64 v[2:3], s[84:85], 0, v[140:141]
	v_lshl_add_u64 v[2:3], v[2:3], 0, s[46:47]
	s_add_i32 m0, s37, 0xc000
	ds_read_b128 v[164:167], v208
	ds_read_b128 v[168:171], v208 offset:1024
	ds_read_b128 v[172:175], v208 offset:2048
	ds_read_b128 v[176:179], v208 offset:3072
	ds_read_b128 v[180:183], v208 offset:4096
	ds_read_b128 v[184:187], v208 offset:5120
	ds_read_b128 v[188:191], v208 offset:6144
	ds_read_b128 v[192:195], v208 offset:7168
	global_load_lds_dwordx4 v[2:3], off
	v_lshl_add_u64 v[2:3], s[84:85], 0, v[142:143]
	v_lshl_add_u64 v[2:3], v[2:3], 0, s[46:47]
	s_add_i32 m0, s37, 0xe000
	s_nop 0
	global_load_lds_dwordx4 v[2:3], off
	s_waitcnt lgkmcnt(8)
	s_setprio 1
	s_barrier
	s_waitcnt lgkmcnt(0)
	v_mfma_f32_16x16x32_bf16 v[128:131], v[148:151], v[164:167], v[128:131]
	v_mfma_f32_16x16x32_bf16 v[124:127], v[156:159], v[164:167], v[124:127]
	v_mfma_f32_16x16x32_bf16 v[112:115], v[148:151], v[172:175], v[112:115]
	v_mfma_f32_16x16x32_bf16 v[108:111], v[156:159], v[172:175], v[108:111]
	v_mfma_f32_16x16x32_bf16 v[96:99], v[148:151], v[180:183], v[96:99]
	v_mfma_f32_16x16x32_bf16 v[92:95], v[156:159], v[180:183], v[92:95]
	v_mfma_f32_16x16x32_bf16 v[80:83], v[148:151], v[188:191], v[80:83]
	v_mfma_f32_16x16x32_bf16 v[76:79], v[156:159], v[188:191], v[76:79]
	v_mfma_f32_16x16x32_bf16 v[128:131], v[152:155], v[168:171], v[128:131]
	v_mfma_f32_16x16x32_bf16 v[124:127], v[160:163], v[168:171], v[124:127]
	v_mfma_f32_16x16x32_bf16 v[112:115], v[152:155], v[176:179], v[112:115]
	v_mfma_f32_16x16x32_bf16 v[108:111], v[160:163], v[176:179], v[108:111]
	v_mfma_f32_16x16x32_bf16 v[96:99], v[152:155], v[184:187], v[96:99]
	v_mfma_f32_16x16x32_bf16 v[92:95], v[160:163], v[184:187], v[92:95]
	v_mfma_f32_16x16x32_bf16 v[80:83], v[152:155], v[192:195], v[80:83]
	v_mfma_f32_16x16x32_bf16 v[76:79], v[160:163], v[192:195], v[76:79]
	s_setprio 0
	s_barrier
	s_add_i32 s14, s70, s58
	v_add_u32_e32 v0, s71, v205
	v_lshl_add_u64 v[200:201], s[48:49], 0, v[134:135]
	s_mov_b32 m0, s14
	ds_read_b128 v[196:199], v0
	ds_read_b128 v[210:213], v0 offset:1024
	ds_read_b128 v[214:217], v0 offset:2048
	ds_read_b128 v[218:221], v0 offset:3072
	global_load_lds_dwordx4 v[200:201], off
	v_lshl_add_u64 v[222:223], s[48:49], 0, v[138:139]
	s_add_i32 m0, s14, 0x2000
	s_nop 0
	global_load_lds_dwordx4 v[222:223], off
	s_setprio 1
	s_barrier
	s_waitcnt lgkmcnt(0)
	v_mfma_f32_16x16x32_bf16 v[120:123], v[196:199], v[164:167], v[120:123]
	v_mfma_f32_16x16x32_bf16 v[116:119], v[214:217], v[164:167], v[116:119]
	v_mfma_f32_16x16x32_bf16 v[104:107], v[196:199], v[172:175], v[104:107]
	v_mfma_f32_16x16x32_bf16 v[100:103], v[214:217], v[172:175], v[100:103]
	v_mfma_f32_16x16x32_bf16 v[88:91], v[196:199], v[180:183], v[88:91]
	v_mfma_f32_16x16x32_bf16 v[84:87], v[214:217], v[180:183], v[84:87]
	v_mfma_f32_16x16x32_bf16 v[72:75], v[196:199], v[188:191], v[72:75]
	v_mfma_f32_16x16x32_bf16 v[68:71], v[214:217], v[188:191], v[68:71]
	v_mfma_f32_16x16x32_bf16 v[120:123], v[210:213], v[168:171], v[120:123]
	v_mfma_f32_16x16x32_bf16 v[116:119], v[218:221], v[168:171], v[116:119]
	v_mfma_f32_16x16x32_bf16 v[104:107], v[210:213], v[176:179], v[104:107]
	v_mfma_f32_16x16x32_bf16 v[100:103], v[218:221], v[176:179], v[100:103]
	v_mfma_f32_16x16x32_bf16 v[88:91], v[210:213], v[184:187], v[88:91]
	v_mfma_f32_16x16x32_bf16 v[84:87], v[218:221], v[184:187], v[84:87]
	v_mfma_f32_16x16x32_bf16 v[72:75], v[210:213], v[192:195], v[72:75]
	v_mfma_f32_16x16x32_bf16 v[68:71], v[218:221], v[192:195], v[68:71]
	s_setprio 0
	s_mov_b32 m0, s37
	v_lshl_add_u64 v[224:225], s[50:51], 0, v[132:133]
	s_barrier
	ds_read_b128 v[164:167], v208 offset:16384
	ds_read_b128 v[168:171], v208 offset:17408
	ds_read_b128 v[172:175], v208 offset:18432
	ds_read_b128 v[176:179], v208 offset:19456
	ds_read_b128 v[180:183], v208 offset:20480
	ds_read_b128 v[184:187], v208 offset:21504
	ds_read_b128 v[188:191], v208 offset:22528
	ds_read_b128 v[192:195], v208 offset:23552
	global_load_lds_dwordx4 v[224:225], off
	v_lshl_add_u64 v[226:227], s[50:51], 0, v[136:137]
	s_mov_b32 m0, s59
	s_nop 0
	global_load_lds_dwordx4 v[226:227], off
	s_setprio 1
	s_barrier
	s_waitcnt lgkmcnt(0)
	v_mfma_f32_16x16x32_bf16 v[64:67], v[148:151], v[164:167], v[64:67]
	v_mfma_f32_16x16x32_bf16 v[60:63], v[156:159], v[164:167], v[60:63]
	v_mfma_f32_16x16x32_bf16 v[48:51], v[148:151], v[172:175], v[48:51]
	v_mfma_f32_16x16x32_bf16 v[44:47], v[156:159], v[172:175], v[44:47]
	v_mfma_f32_16x16x32_bf16 v[32:35], v[148:151], v[180:183], v[32:35]
	v_mfma_f32_16x16x32_bf16 v[28:31], v[156:159], v[180:183], v[28:31]
	v_mfma_f32_16x16x32_bf16 v[16:19], v[148:151], v[188:191], v[16:19]
	v_mfma_f32_16x16x32_bf16 v[12:15], v[156:159], v[188:191], v[12:15]
	v_mfma_f32_16x16x32_bf16 v[64:67], v[152:155], v[168:171], v[64:67]
	v_mfma_f32_16x16x32_bf16 v[60:63], v[160:163], v[168:171], v[60:63]
	v_mfma_f32_16x16x32_bf16 v[48:51], v[152:155], v[176:179], v[48:51]
	v_mfma_f32_16x16x32_bf16 v[44:47], v[160:163], v[176:179], v[44:47]
	v_mfma_f32_16x16x32_bf16 v[32:35], v[152:155], v[184:187], v[32:35]
	v_mfma_f32_16x16x32_bf16 v[28:31], v[160:163], v[184:187], v[28:31]
	v_mfma_f32_16x16x32_bf16 v[16:19], v[152:155], v[192:195], v[16:19]
	v_mfma_f32_16x16x32_bf16 v[12:15], v[160:163], v[192:195], v[12:15]
	s_setprio 0
	s_barrier
; #define PG8_STAGE(bufoff, gbase, voff) do { _Pragma("unroll") for (int _i = 0; _i < 2; ++_i) \
;         __builtin_amdgcn_global_load_lds((const unsigned*)((const char*)(gbase) + (voff)[_i]), (LAS unsigned*)(lds + (bufoff) + ldsw + _i * 8192), 16, 0, 0); } while (0)
; #define PG8_LDA(dst, b, h) do { _Pragma("unroll") for (int m = 0; m < 4; ++m) _Pragma("unroll") for (int k = 0; k < 2; ++k) dst[m][k] = *(const LAS bf16x8*)(lds + PG8_SA(b, h) + aoff + m * 2048 + k * 1024); } while (0)
; #define PG8_LDB(dst, b, h) do { _Pragma("unroll") for (int n = 0; n < 2; ++n) _Pragma("unroll") for (int k = 0; k < 2; ++k) dst[n][k] = *(const LAS bf16x8*)(lds + PG8_SB(b, h) + boff + n * 2048 + k * 1024); } while (0)
; #define PG8_MMA(ai, bj, At, Bt) do { __builtin_amdgcn_s_setprio(1); _Pragma("unroll") for (int m = 0; m < 4; ++m) _Pragma("unroll") for (int n = 0; n < 2; ++n) _Pragma("unroll") for (int k = 0; k < 2; ++k) \
;         acc[ai][bj][m][n] = __builtin_amdgcn_mfma_f32_16x16x32_bf16(Bt[n][k], At[m][k], acc[ai][bj][m][n], 0, 0, 0); __builtin_amdgcn_s_setprio(0); } while (0)
; #define PG8_WAIT_V(n) asm volatile("s_waitcnt vmcnt(" #n ")" ::: "memory")
; #define PG8_WAIT_L(n) asm volatile("s_waitcnt lgkmcnt(" #n ")" ::: "memory")
; #define PG8_BAR __builtin_amdgcn_s_barrier()
; #define PG8_SCHED __builtin_amdgcn_sched_barrier(0)
; template <class Epi>
; DI void gemm_phase(LAS unsigned char* lds, const Gemm g, const StaticOrder& S_, const Epi& E) {
;     ...
;             PG8_BAR; PG8_WAIT_L(0); PG8_MMA(1, 0, At, B0); PG8_BAR; PG8_SCHED;
;             PG8_STAGE(PG8_SB(0, 1), b2 + hstepB, voffB);
;             PG8_WAIT_V(6); PG8_BAR; PG8_MMA(1, 1, At, B1); PG8_BAR;
;             PG8_LDB(B0, 1, 0); PG8_SCHED; PG8_LDA(At, 1, 0); PG8_STAGE(PG8_SA(0, 1), a2 + hstepA, voffA);
;             PG8_WAIT_L(8); PG8_BAR; PG8_WAIT_L(0); PG8_MMA(0, 0, At, B0); PG8_BAR; PG8_SCHED;
;             PG8_LDB(B1, 1, 1); PG8_STAGE(PG8_SB(1, 0), b3, voffB);
;             PG8_BAR; PG8_WAIT_L(0); PG8_MMA(0, 1, At, B1); PG8_BAR;
;             PG8_LDA(At, 1, 1); PG8_STAGE(PG8_SA(1, 0), a3, voffA);
;             PG8_BAR; PG8_WAIT_L(0); PG8_MMA(1, 0, At, B0); PG8_BAR; PG8_SCHED;
	s_add_u32 s84, s48, 0x80000
	s_addc_u32 s85, s49, 0
	s_add_i32 s14, s71, s58
	v_lshl_add_u64 v[2:3], s[84:85], 0, v[134:135]
	s_mov_b32 m0, s14
	s_nop 0
	global_load_lds_dwordx4 v[2:3], off
	v_lshl_add_u64 v[2:3], s[84:85], 0, v[138:139]
	s_add_i32 m0, s14, 0x2000
	s_nop 0
	global_load_lds_dwordx4 v[2:3], off
	s_waitcnt vmcnt(6)
	s_setprio 1
	s_barrier
	v_mfma_f32_16x16x32_bf16 v[56:59], v[196:199], v[164:167], v[56:59]
	v_mfma_f32_16x16x32_bf16 v[52:55], v[214:217], v[164:167], v[52:55]
	v_mfma_f32_16x16x32_bf16 v[40:43], v[196:199], v[172:175], v[40:43]
	v_mfma_f32_16x16x32_bf16 v[36:39], v[214:217], v[172:175], v[36:39]
	v_mfma_f32_16x16x32_bf16 v[24:27], v[196:199], v[180:183], v[24:27]
	v_mfma_f32_16x16x32_bf16 v[20:23], v[214:217], v[180:183], v[20:23]
	v_mfma_f32_16x16x32_bf16 v[8:11], v[196:199], v[188:191], v[8:11]
	v_mfma_f32_16x16x32_bf16 v[2:5], v[214:217], v[188:191], v[4:7]
	v_mfma_f32_16x16x32_bf16 v[56:59], v[210:213], v[168:171], v[56:59]
	v_mfma_f32_16x16x32_bf16 v[52:55], v[218:221], v[168:171], v[52:55]
	v_mfma_f32_16x16x32_bf16 v[40:43], v[210:213], v[176:179], v[40:43]
	v_mfma_f32_16x16x32_bf16 v[36:39], v[218:221], v[176:179], v[36:39]
	v_mfma_f32_16x16x32_bf16 v[24:27], v[210:213], v[184:187], v[24:27]
	v_mfma_f32_16x16x32_bf16 v[20:23], v[218:221], v[184:187], v[20:23]
	v_mfma_f32_16x16x32_bf16 v[8:11], v[210:213], v[192:195], v[8:11]
	v_mfma_f32_16x16x32_bf16 v[2:5], v[218:221], v[192:195], v[2:5]
	s_setprio 0
	s_add_i32 s14, 0, 0x18000
	v_add_u32_e32 v0, s14, v205
	s_barrier
	ds_read_b128 v[148:151], v0
	ds_read_b128 v[152:155], v0 offset:1024
	ds_read_b128 v[156:159], v0 offset:2048
	ds_read_b128 v[160:163], v0 offset:3072
	s_add_u32 s50, s50, 0x80000
	s_addc_u32 s51, s51, 0
	s_mov_b32 m0, s60
	v_lshl_add_u64 v[6:7], s[50:51], 0, v[132:133]
	ds_read_b128 v[164:167], v208 offset:32768
	ds_read_b128 v[168:171], v208 offset:33792
	ds_read_b128 v[172:175], v208 offset:34816
	ds_read_b128 v[176:179], v208 offset:35840
	ds_read_b128 v[180:183], v208 offset:36864
	ds_read_b128 v[184:187], v208 offset:37888
	ds_read_b128 v[188:191], v208 offset:38912
	ds_read_b128 v[192:195], v208 offset:39936
	global_load_lds_dwordx4 v[6:7], off
	v_lshl_add_u64 v[6:7], s[50:51], 0, v[136:137]
	s_mov_b32 m0, s61
	s_nop 0
	global_load_lds_dwordx4 v[6:7], off
	s_waitcnt lgkmcnt(8)
	s_setprio 1
	s_barrier
	s_waitcnt lgkmcnt(0)
	v_mfma_f32_16x16x32_bf16 v[128:131], v[148:151], v[164:167], v[128:131]
	v_mfma_f32_16x16x32_bf16 v[124:127], v[156:159], v[164:167], v[124:127]
	v_mfma_f32_16x16x32_bf16 v[112:115], v[148:151], v[172:175], v[112:115]
	v_mfma_f32_16x16x32_bf16 v[108:111], v[156:159], v[172:175], v[108:111]
	v_mfma_f32_16x16x32_bf16 v[96:99], v[148:151], v[180:183], v[96:99]
	v_mfma_f32_16x16x32_bf16 v[92:95], v[156:159], v[180:183], v[92:95]
	v_mfma_f32_16x16x32_bf16 v[80:83], v[148:151], v[188:191], v[80:83]
	v_mfma_f32_16x16x32_bf16 v[76:79], v[156:159], v[188:191], v[76:79]
	v_mfma_f32_16x16x32_bf16 v[128:131], v[152:155], v[168:171], v[128:131]
	v_mfma_f32_16x16x32_bf16 v[124:127], v[160:163], v[168:171], v[124:127]
	v_mfma_f32_16x16x32_bf16 v[112:115], v[152:155], v[176:179], v[112:115]
	v_mfma_f32_16x16x32_bf16 v[108:111], v[160:163], v[176:179], v[108:111]
	v_mfma_f32_16x16x32_bf16 v[96:99], v[152:155], v[184:187], v[96:99]
	v_mfma_f32_16x16x32_bf16 v[92:95], v[160:163], v[184:187], v[92:95]
	v_mfma_f32_16x16x32_bf16 v[80:83], v[152:155], v[192:195], v[80:83]
	v_mfma_f32_16x16x32_bf16 v[76:79], v[160:163], v[192:195], v[76:79]
	s_setprio 0
	s_barrier
	s_add_i32 s50, 0, 0x1c000
	s_add_i32 s14, s14, s58
	v_add_u32_e32 v0, s50, v205
	v_lshl_add_u64 v[6:7], v[200:201], 0, s[16:17]
	s_mov_b32 m0, s14
	ds_read_b128 v[196:199], v0
	ds_read_b128 v[210:213], v0 offset:1024
	ds_read_b128 v[214:217], v0 offset:2048
	ds_read_b128 v[218:221], v0 offset:3072
	global_load_lds_dwordx4 v[6:7], off
	v_lshl_add_u64 v[6:7], v[222:223], 0, s[16:17]
	s_add_i32 m0, s14, 0x2000
	s_nop 0
	global_load_lds_dwordx4 v[6:7], off
	s_setprio 1
	s_barrier
	s_waitcnt lgkmcnt(0)
	v_mfma_f32_16x16x32_bf16 v[120:123], v[196:199], v[164:167], v[120:123]
	v_mfma_f32_16x16x32_bf16 v[116:119], v[214:217], v[164:167], v[116:119]
	v_mfma_f32_16x16x32_bf16 v[104:107], v[196:199], v[172:175], v[104:107]
	v_mfma_f32_16x16x32_bf16 v[100:103], v[214:217], v[172:175], v[100:103]
	v_mfma_f32_16x16x32_bf16 v[88:91], v[196:199], v[180:183], v[88:91]
	v_mfma_f32_16x16x32_bf16 v[84:87], v[214:217], v[180:183], v[84:87]
	v_mfma_f32_16x16x32_bf16 v[72:75], v[196:199], v[188:191], v[72:75]
	v_mfma_f32_16x16x32_bf16 v[68:71], v[214:217], v[188:191], v[68:71]
	v_mfma_f32_16x16x32_bf16 v[120:123], v[210:213], v[168:171], v[120:123]
	v_mfma_f32_16x16x32_bf16 v[116:119], v[218:221], v[168:171], v[116:119]
	v_mfma_f32_16x16x32_bf16 v[104:107], v[210:213], v[176:179], v[104:107]
	v_mfma_f32_16x16x32_bf16 v[100:103], v[218:221], v[176:179], v[100:103]
	v_mfma_f32_16x16x32_bf16 v[88:91], v[210:213], v[184:187], v[88:91]
	v_mfma_f32_16x16x32_bf16 v[84:87], v[218:221], v[184:187], v[84:87]
	v_mfma_f32_16x16x32_bf16 v[72:75], v[210:213], v[192:195], v[72:75]
	v_mfma_f32_16x16x32_bf16 v[68:71], v[218:221], v[192:195], v[68:71]
	s_setprio 0
	s_mov_b32 m0, s66
	v_lshl_add_u64 v[6:7], v[224:225], 0, s[16:17]
	s_barrier
	ds_read_b128 v[164:167], v208 offset:49152
	ds_read_b128 v[168:171], v208 offset:50176
	ds_read_b128 v[172:175], v208 offset:51200
	ds_read_b128 v[176:179], v208 offset:52224
	ds_read_b128 v[180:183], v208 offset:53248
	ds_read_b128 v[184:187], v208 offset:54272
	ds_read_b128 v[188:191], v208 offset:55296
	ds_read_b128 v[192:195], v208 offset:56320
	global_load_lds_dwordx4 v[6:7], off
	v_lshl_add_u64 v[6:7], v[226:227], 0, s[16:17]
	s_mov_b32 m0, s67
	s_nop 0
	global_load_lds_dwordx4 v[6:7], off
	s_setprio 1
	s_barrier
; #define PG8_STAGE(bufoff, gbase, voff) do { _Pragma("unroll") for (int _i = 0; _i < 2; ++_i) \
;         __builtin_amdgcn_global_load_lds((const unsigned*)((const char*)(gbase) + (voff)[_i]), (LAS unsigned*)(lds + (bufoff) + ldsw + _i * 8192), 16, 0, 0); } while (0)
; #define PG8_MMA(ai, bj, At, Bt) do { __builtin_amdgcn_s_setprio(1); _Pragma("unroll") for (int m = 0; m < 4; ++m) _Pragma("unroll") for (int n = 0; n < 2; ++n) _Pragma("unroll") for (int k = 0; k < 2; ++k) \
;         acc[ai][bj][m][n] = __builtin_amdgcn_mfma_f32_16x16x32_bf16(Bt[n][k], At[m][k], acc[ai][bj][m][n], 0, 0, 0); __builtin_amdgcn_s_setprio(0); } while (0)
; #define PG8_WAIT_V(n) asm volatile("s_waitcnt vmcnt(" #n ")" ::: "memory")
; #define PG8_WAIT_L(n) asm volatile("s_waitcnt lgkmcnt(" #n ")" ::: "memory")
; #define PG8_BAR __builtin_amdgcn_s_barrier()
; #define PG8_SCHED __builtin_amdgcn_sched_barrier(0)
; template <class Epi>
; DI void gemm_phase(LAS unsigned char* lds, const Gemm g, const StaticOrder& S_, const Epi& E) {
;     ...
;             PG8_BAR; PG8_WAIT_L(0); PG8_MMA(1, 0, At, B0); PG8_BAR; PG8_SCHED;
;             PG8_STAGE(PG8_SB(1, 1), b3 + hstepB, voffB);
;             PG8_WAIT_V(6); PG8_BAR; PG8_MMA(1, 1, At, B1); PG8_BAR;
;         }
;         if constexpr (Epi::MID) { if (hf == 0) E.mid(acc, cur, wr, wc, fr, fq); }
;     DI void mid(f32x4 (&acc)[2][2][4][2], const pg8::Unit& u, int wr, int wc, int fr, int fq) const {
;     ...
;         unsigned b0_ = (unsigned)u.pn * (unsigned)(S * 256) + (unsigned)(u.pm * 256 + wr * 64 + fr) * 256u + (unsigned)(wc * 32 + 8 * fq);
;         asm volatile("" : "+v"(b0_));
;         u32x2 g1[2][4][2], g2[2][4][2];
; #pragma unroll
;         for (int ai = 0; ai < 2; ++ai)
; #pragma unroll
;             for (int m = 0; m < 4; ++m)
; #pragma unroll
;                 for (int bj = 0; bj < 2; ++bj) { const unsigned bo = b0_ + (unsigned)(ai * 128 + m * 16) * 256u + bj * 128u;
;                     g1[ai][m][bj] = *(const u32x2*)(zm + bo); g2[ai][m][bj] = *(const u32x2*)(zm + bo + (unsigned)(8 * S * 256)); }
	s_waitcnt lgkmcnt(0)
	v_mfma_f32_16x16x32_bf16 v[64:67], v[148:151], v[164:167], v[64:67]
	v_mfma_f32_16x16x32_bf16 v[60:63], v[156:159], v[164:167], v[60:63]
	v_mfma_f32_16x16x32_bf16 v[48:51], v[148:151], v[172:175], v[48:51]
	v_mfma_f32_16x16x32_bf16 v[44:47], v[156:159], v[172:175], v[44:47]
	v_mfma_f32_16x16x32_bf16 v[32:35], v[148:151], v[180:183], v[32:35]
	v_mfma_f32_16x16x32_bf16 v[28:31], v[156:159], v[180:183], v[28:31]
	v_mfma_f32_16x16x32_bf16 v[16:19], v[148:151], v[188:191], v[16:19]
	v_mfma_f32_16x16x32_bf16 v[12:15], v[156:159], v[188:191], v[12:15]
	v_mfma_f32_16x16x32_bf16 v[64:67], v[152:155], v[168:171], v[64:67]
	v_mfma_f32_16x16x32_bf16 v[60:63], v[160:163], v[168:171], v[60:63]
	v_mfma_f32_16x16x32_bf16 v[48:51], v[152:155], v[176:179], v[48:51]
	v_mfma_f32_16x16x32_bf16 v[44:47], v[160:163], v[176:179], v[44:47]
	v_mfma_f32_16x16x32_bf16 v[32:35], v[152:155], v[184:187], v[32:35]
	v_mfma_f32_16x16x32_bf16 v[28:31], v[160:163], v[184:187], v[28:31]
	v_mfma_f32_16x16x32_bf16 v[16:19], v[152:155], v[192:195], v[16:19]
	v_mfma_f32_16x16x32_bf16 v[12:15], v[160:163], v[192:195], v[12:15]
	s_setprio 0
	s_barrier
	s_add_u32 s48, s48, 0x80080
	s_addc_u32 s49, s49, 0
	s_add_i32 s14, s50, s58
	v_lshl_add_u64 v[6:7], s[48:49], 0, v[134:135]
	s_mov_b32 m0, s14
	s_nop 0
	global_load_lds_dwordx4 v[6:7], off
	v_lshl_add_u64 v[6:7], s[48:49], 0, v[138:139]
	s_add_i32 m0, s14, 0x2000
	s_nop 0
	global_load_lds_dwordx4 v[6:7], off
	s_waitcnt vmcnt(6)
	s_setprio 1
	s_barrier
	v_mfma_f32_16x16x32_bf16 v[56:59], v[196:199], v[164:167], v[56:59]
	v_mfma_f32_16x16x32_bf16 v[52:55], v[214:217], v[164:167], v[52:55]
	v_mfma_f32_16x16x32_bf16 v[40:43], v[196:199], v[172:175], v[40:43]
	v_mfma_f32_16x16x32_bf16 v[36:39], v[214:217], v[172:175], v[36:39]
	v_mfma_f32_16x16x32_bf16 v[24:27], v[196:199], v[180:183], v[24:27]
	v_mfma_f32_16x16x32_bf16 v[20:23], v[214:217], v[180:183], v[20:23]
	v_mfma_f32_16x16x32_bf16 v[6:9], v[196:199], v[188:191], v[8:11]
	v_mfma_f32_16x16x32_bf16 v[2:5], v[214:217], v[188:191], v[2:5]
	v_mfma_f32_16x16x32_bf16 v[56:59], v[210:213], v[168:171], v[56:59]
	v_mfma_f32_16x16x32_bf16 v[52:55], v[218:221], v[168:171], v[52:55]
	v_mfma_f32_16x16x32_bf16 v[40:43], v[210:213], v[176:179], v[40:43]
	v_mfma_f32_16x16x32_bf16 v[36:39], v[218:221], v[176:179], v[36:39]
	v_mfma_f32_16x16x32_bf16 v[24:27], v[210:213], v[184:187], v[24:27]
	v_mfma_f32_16x16x32_bf16 v[20:23], v[218:221], v[184:187], v[20:23]
	v_mfma_f32_16x16x32_bf16 v[8:11], v[210:213], v[192:195], v[6:9]
	v_mfma_f32_16x16x32_bf16 v[4:7], v[218:221], v[192:195], v[2:5]
	s_setprio 0
	s_add_u32 s46, s46, 0x100
	s_addc_u32 s47, s47, 0
	s_cmp_ge_u32 s82, s81
	s_mov_b32 s14, s82
	s_barrier
	s_cbranch_scc0 .LBB0_450
	s_and_b64 vcc, exec, s[44:45]
	s_cbranch_vccz .LBB0_448
	v_mov_b32_e32 v0, v209
	v_mov_b32_e32 v149, v1
	v_lshl_add_u64 v[2:3], s[18:19], 0, v[0:1]
	v_add_co_u32_e32 v2, vcc, 0x2000000, v2
	v_add_u32_e32 v148, 0x80, v0
	s_nop 0
	v_addc_co_u32_e32 v3, vcc, 0, v3, vcc
	v_lshl_add_u64 v[150:151], s[18:19], 0, v[148:149]
	v_add_co_u32_e32 v150, vcc, 0x2000000, v150
	v_add_u32_e32 v154, 0x1080, v0
	s_nop 0
	v_addc_co_u32_e32 v151, vcc, 0, v151, vcc
	global_load_dwordx2 v[200:201], v[150:151], off
	v_add_u32_e32 v150, 0x1000, v0
	v_mov_b32_e32 v151, v1
	v_lshl_add_u64 v[152:153], s[18:19], 0, v[150:151]
	v_add_co_u32_e32 v152, vcc, 0x2000000, v152
	v_mov_b32_e32 v155, v1
	s_nop 0
	v_addc_co_u32_e32 v153, vcc, 0, v153, vcc
	v_lshl_add_u64 v[156:157], s[18:19], 0, v[154:155]
	v_add_co_u32_e32 v156, vcc, 0x2000000, v156
	v_add_u32_e32 v158, 0x2000, v0
	v_mov_b32_e32 v159, v1
	v_addc_co_u32_e32 v157, vcc, 0, v157, vcc
	v_lshl_add_u64 v[160:161], s[18:19], 0, v[158:159]
	global_load_dwordx2 v[210:211], v148, s[18:19]
	global_load_dwordx2 v[196:197], v150, s[18:19]
	global_load_dwordx2 v[192:193], v154, s[18:19]
	global_load_dwordx2 v[188:189], v158, s[18:19]
	v_add_co_u32_e32 v148, vcc, 0x2000000, v160
	v_add_u32_e32 v150, 0x3000, v0
	s_nop 0
	v_addc_co_u32_e32 v149, vcc, 0, v161, vcc
	global_load_dwordx2 v[212:213], v0, s[18:19]
	global_load_dwordx2 v[214:215], v[2:3], off
	global_load_dwordx2 v[198:199], v[152:153], off
	global_load_dwordx2 v[190:191], v[148:149], off
	v_add_u32_e32 v2, 0x2080, v0
	v_mov_b32_e32 v3, v1
	v_lshl_add_u64 v[148:149], s[18:19], 0, v[2:3]
	v_add_co_u32_e32 v148, vcc, 0x2000000, v148
	v_lshl_add_u64 v[152:153], s[18:19], 0, v[150:151]
	s_nop 0
	v_addc_co_u32_e32 v149, vcc, 0, v149, vcc
	v_add_co_u32_e32 v152, vcc, 0x2000000, v152
	v_add_u32_e32 v154, 0x3080, v0
	s_nop 0
	v_addc_co_u32_e32 v153, vcc, 0, v153, vcc
	v_lshl_add_u64 v[158:159], s[18:19], 0, v[154:155]
	v_add_co_u32_e32 v158, vcc, 0x2000000, v158
	v_add_u32_e32 v160, 0x8000, v0
	v_mov_b32_e32 v161, v1
	v_addc_co_u32_e32 v159, vcc, 0, v159, vcc
	v_lshl_add_u64 v[162:163], s[18:19], 0, v[160:161]
	global_load_dwordx2 v[186:187], v2, s[18:19]
	global_load_dwordx2 v[182:183], v150, s[18:19]
	global_load_dwordx2 v[178:179], v154, s[18:19]
	global_load_dwordx2 v[174:175], v160, s[18:19]
	v_add_co_u32_e32 v2, vcc, 0x2000000, v162
	v_add_u32_e32 v150, 0x8080, v0
	s_nop 0
	v_addc_co_u32_e32 v3, vcc, 0, v163, vcc
	v_lshl_add_u64 v[154:155], s[18:19], 0, v[150:151]
	v_add_co_u32_e32 v154, vcc, 0x2000000, v154
	s_waitcnt vmcnt(0)
; DI float rcpf_(float x) { return __builtin_amdgcn_rcpf(x); }
; DI float ub(unsigned w, int i) { return (float)((w >> (8 * i)) & 0xffu); }
;     DI void mid(f32x4 (&acc)[2][2][4][2], const pg8::Unit& u, int wr, int wc, int fr, int fq) const {
;     ...
;                 for (int bj = 0; bj < 2; ++bj) { const unsigned bo = b0_ + (unsigned)(ai * 128 + m * 16) * 256u + bj * 128u;
;                     g1[ai][m][bj] = *(const u32x2*)(zm + bo); g2[ai][m][bj] = *(const u32x2*)(zm + bo + (unsigned)(8 * S * 256)); }
; #pragma unroll
;         for (int ai = 0; ai < 2; ++ai)
; #pragma unroll
;             for (int m = 0; m < 4; ++m)
; #pragma unroll
;                 for (int bj = 0; bj < 2; ++bj)
; #pragma unroll
;                     for (int e = 0; e < 8; ++e)
;                         acc[ai][bj][m][e >> 2][e & 3] *= ub(g1[ai][m][bj][e >> 2], e & 3) * rcpf_(ub(g2[ai][m][bj][e >> 2], e & 3));
	v_cvt_f32_ubyte1_e32 v225, v212
	v_addc_co_u32_e32 v155, vcc, 0, v155, vcc
	global_load_dwordx2 v[184:185], v[152:153], off
	global_load_dwordx2 v[180:181], v[158:159], off
	global_load_dwordx2 v[176:177], v[2:3], off
	global_load_dwordx2 v[170:171], v[154:155], off
	v_add_u32_e32 v2, 0x9000, v0
	v_mov_b32_e32 v3, v1
	v_lshl_add_u64 v[152:153], s[18:19], 0, v[2:3]
	v_add_co_u32_e32 v152, vcc, 0x2000000, v152
	v_add_u32_e32 v154, 0x9080, v0
	v_mov_b32_e32 v155, v1
	v_addc_co_u32_e32 v153, vcc, 0, v153, vcc
	v_lshl_add_u64 v[158:159], s[18:19], 0, v[154:155]
	v_add_co_u32_e32 v160, vcc, 0x2000000, v158
	v_add_u32_e32 v158, 0xa000, v0
	s_nop 0
	v_addc_co_u32_e32 v161, vcc, 0, v159, vcc
	v_mov_b32_e32 v159, v1
	v_lshl_add_u64 v[164:165], s[18:19], 0, v[158:159]
	global_load_dwordx2 v[172:173], v150, s[18:19]
	global_load_dwordx2 v[166:167], v2, s[18:19]
	global_load_dwordx2 v[162:163], v154, s[18:19]
	s_nop 0
	global_load_dwordx2 v[158:159], v158, s[18:19]
	v_add_co_u32_e32 v2, vcc, 0x2000000, v164
	v_add_u32_e32 v150, 0xa080, v0
	s_nop 0
	v_addc_co_u32_e32 v3, vcc, 0, v165, vcc
	v_lshl_add_u64 v[154:155], s[18:19], 0, v[150:151]
	v_add_co_u32_e32 v154, vcc, 0x2000000, v154
	v_cvt_f32_ubyte0_e32 v224, v212
	s_nop 0
	v_addc_co_u32_e32 v155, vcc, 0, v155, vcc
	global_load_dwordx2 v[168:169], v[152:153], off
	global_load_dwordx2 v[164:165], v[160:161], off
	s_nop 0
	global_load_dwordx2 v[160:161], v[2:3], off
	s_nop 0
	global_load_dwordx2 v[154:155], v[154:155], off
	v_add_u32_e32 v152, 0xb000, v0
	v_mov_b32_e32 v153, v1
	v_lshl_add_u64 v[2:3], s[18:19], 0, v[152:153]
	v_add_co_u32_e32 v216, vcc, 0x2000000, v2
	v_add_u32_e32 v0, 0xb080, v0
	s_nop 0
	v_addc_co_u32_e32 v217, vcc, 0, v3, vcc
	global_load_dwordx2 v[220:221], v[156:157], off
	global_load_dwordx2 v[194:195], v[148:149], off
	global_load_dwordx2 v[2:3], v0, s[18:19]
	v_lshl_add_u64 v[218:219], s[18:19], 0, v[0:1]
	v_add_co_u32_e32 v148, vcc, 0x2000000, v218
	v_cvt_f32_ubyte0_e32 v0, v214
	s_nop 0
	v_addc_co_u32_e32 v149, vcc, 0, v219, vcc
	global_load_dwordx2 v[156:157], v150, s[18:19]
	s_nop 0
	global_load_dwordx2 v[150:151], v152, s[18:19]
	s_nop 0
	global_load_dwordx2 v[152:153], v[216:217], off
	s_nop 0
	global_load_dwordx2 v[148:149], v[148:149], off
	v_rcp_iflag_f32_e32 v216, v0
	v_cvt_f32_ubyte1_e32 v0, v214
	v_rcp_iflag_f32_e32 v217, v0
	v_cvt_f32_ubyte2_e32 v0, v214
	v_rcp_iflag_f32_e32 v218, v0
	v_cvt_f32_ubyte3_e32 v0, v214
	v_rcp_iflag_f32_e32 v219, v0
	v_pk_mul_f32 v[216:217], v[216:217], v[224:225]
	v_cvt_f32_ubyte0_e32 v0, v215
	v_pk_mul_f32 v[128:129], v[128:129], v[216:217]
	v_rcp_iflag_f32_e32 v216, v0
	v_cvt_f32_ubyte1_e32 v0, v215
	v_rcp_iflag_f32_e32 v217, v0
	v_cvt_f32_ubyte3_e32 v223, v212
	v_cvt_f32_ubyte2_e32 v222, v212
	v_cvt_f32_ubyte2_e32 v0, v215
	v_pk_mul_f32 v[218:219], v[218:219], v[222:223]
	v_rcp_iflag_f32_e32 v214, v0
	v_cvt_f32_ubyte3_e32 v0, v215
	v_cvt_f32_ubyte1_e32 v223, v213
	v_cvt_f32_ubyte0_e32 v222, v213
	v_pk_mul_f32 v[130:131], v[130:131], v[218:219]
	v_rcp_iflag_f32_e32 v215, v0
	v_cvt_f32_ubyte3_e32 v219, v213
	v_cvt_f32_ubyte2_e32 v218, v213
	v_pk_mul_f32 v[212:213], v[216:217], v[222:223]
	v_cvt_f32_ubyte0_e32 v0, v200
	v_pk_mul_f32 v[124:125], v[124:125], v[212:213]
	v_rcp_iflag_f32_e32 v212, v0
	v_cvt_f32_ubyte1_e32 v0, v200
	v_rcp_iflag_f32_e32 v213, v0
	v_pk_mul_f32 v[214:215], v[214:215], v[218:219]
	v_cvt_f32_ubyte2_e32 v0, v200
	v_pk_mul_f32 v[126:127], v[126:127], v[214:215]
	v_rcp_iflag_f32_e32 v214, v0
	v_cvt_f32_ubyte3_e32 v0, v200
	v_cvt_f32_ubyte1_e32 v219, v210
	v_cvt_f32_ubyte0_e32 v218, v210
	v_rcp_iflag_f32_e32 v215, v0
	v_pk_mul_f32 v[212:213], v[212:213], v[218:219]
	v_cvt_f32_ubyte0_e32 v0, v201
	v_pk_mul_f32 v[120:121], v[120:121], v[212:213]
	v_rcp_iflag_f32_e32 v212, v0
	v_cvt_f32_ubyte1_e32 v0, v201
	v_rcp_iflag_f32_e32 v213, v0
	v_cvt_f32_ubyte2_e32 v0, v201
	v_rcp_iflag_f32_e32 v200, v0
	v_cvt_f32_ubyte3_e32 v0, v201
	v_rcp_iflag_f32_e32 v201, v0
	v_cvt_f32_ubyte3_e32 v217, v210
	v_cvt_f32_ubyte2_e32 v216, v210
	v_pk_mul_f32 v[214:215], v[214:215], v[216:217]
	v_cvt_f32_ubyte0_e32 v0, v198
	v_pk_mul_f32 v[122:123], v[122:123], v[214:215]
	v_cvt_f32_ubyte3_e32 v215, v211
	v_cvt_f32_ubyte2_e32 v214, v211
	v_pk_mul_f32 v[200:201], v[200:201], v[214:215]
	v_cvt_f32_ubyte1_e32 v217, v211
	v_pk_mul_f32 v[118:119], v[118:119], v[200:201]
	v_rcp_iflag_f32_e32 v200, v0
	v_cvt_f32_ubyte1_e32 v0, v198
	v_rcp_iflag_f32_e32 v201, v0
	v_cvt_f32_ubyte0_e32 v216, v211
	v_pk_mul_f32 v[210:211], v[212:213], v[216:217]
	v_cvt_f32_ubyte2_e32 v0, v198
	v_pk_mul_f32 v[116:117], v[116:117], v[210:211]
	v_rcp_iflag_f32_e32 v210, v0
	v_cvt_f32_ubyte3_e32 v0, v198
	v_cvt_f32_ubyte1_e32 v215, v196
	v_cvt_f32_ubyte0_e32 v214, v196
	v_rcp_iflag_f32_e32 v211, v0
	v_pk_mul_f32 v[200:201], v[200:201], v[214:215]
	v_cvt_f32_ubyte0_e32 v0, v199
	v_pk_mul_f32 v[112:113], v[112:113], v[200:201]
	v_rcp_iflag_f32_e32 v200, v0
	v_cvt_f32_ubyte1_e32 v0, v199
	v_rcp_iflag_f32_e32 v201, v0
	v_cvt_f32_ubyte3_e32 v213, v196
	v_cvt_f32_ubyte2_e32 v212, v196
	v_cvt_f32_ubyte2_e32 v0, v199
	v_pk_mul_f32 v[210:211], v[210:211], v[212:213]
	v_rcp_iflag_f32_e32 v198, v0
	v_cvt_f32_ubyte3_e32 v0, v199
	v_cvt_f32_ubyte1_e32 v213, v197
	v_cvt_f32_ubyte0_e32 v212, v197
	v_pk_mul_f32 v[114:115], v[114:115], v[210:211]
	v_rcp_iflag_f32_e32 v199, v0
	v_cvt_f32_ubyte3_e32 v211, v197
	v_cvt_f32_ubyte2_e32 v210, v197
	v_pk_mul_f32 v[196:197], v[200:201], v[212:213]
	s_waitcnt vmcnt(0)
; DI float rcpf_(float x) { return __builtin_amdgcn_rcpf(x); }
; DI float ub(unsigned w, int i) { return (float)((w >> (8 * i)) & 0xffu); }
;     DI void mid(f32x4 (&acc)[2][2][4][2], const pg8::Unit& u, int wr, int wc, int fr, int fq) const {
;     ...
; #pragma unroll
;                     for (int e = 0; e < 8; ++e)
;                         acc[ai][bj][m][e >> 2][e & 3] *= ub(g1[ai][m][bj][e >> 2], e & 3) * rcpf_(ub(g2[ai][m][bj][e >> 2], e & 3));
	v_cvt_f32_ubyte0_e32 v0, v220
	v_pk_mul_f32 v[108:109], v[108:109], v[196:197]
	v_rcp_iflag_f32_e32 v196, v0
	v_cvt_f32_ubyte1_e32 v0, v220
	v_rcp_iflag_f32_e32 v197, v0
	v_pk_mul_f32 v[198:199], v[198:199], v[210:211]
	v_cvt_f32_ubyte2_e32 v0, v220
	v_pk_mul_f32 v[110:111], v[110:111], v[198:199]
	v_rcp_iflag_f32_e32 v198, v0
	v_cvt_f32_ubyte3_e32 v0, v220
	v_cvt_f32_ubyte1_e32 v211, v192
	v_cvt_f32_ubyte0_e32 v210, v192
	v_rcp_iflag_f32_e32 v199, v0
	v_pk_mul_f32 v[196:197], v[196:197], v[210:211]
	v_cvt_f32_ubyte0_e32 v0, v221
	v_pk_mul_f32 v[104:105], v[104:105], v[196:197]
	v_rcp_iflag_f32_e32 v196, v0
	v_cvt_f32_ubyte1_e32 v0, v221
	v_rcp_iflag_f32_e32 v197, v0
	v_cvt_f32_ubyte3_e32 v201, v192
	v_cvt_f32_ubyte2_e32 v200, v192
	v_pk_mul_f32 v[198:199], v[198:199], v[200:201]
	v_cvt_f32_ubyte2_e32 v0, v221
	v_pk_mul_f32 v[106:107], v[106:107], v[198:199]
	v_rcp_iflag_f32_e32 v198, v0
	v_cvt_f32_ubyte3_e32 v0, v221
	v_cvt_f32_ubyte1_e32 v211, v193
	v_cvt_f32_ubyte0_e32 v210, v193
	v_rcp_iflag_f32_e32 v199, v0
	v_cvt_f32_ubyte3_e32 v201, v193
	v_cvt_f32_ubyte2_e32 v200, v193
	v_pk_mul_f32 v[192:193], v[196:197], v[210:211]
	v_cvt_f32_ubyte0_e32 v0, v190
	v_pk_mul_f32 v[100:101], v[100:101], v[192:193]
	v_rcp_iflag_f32_e32 v192, v0
	v_cvt_f32_ubyte1_e32 v0, v190
	v_rcp_iflag_f32_e32 v193, v0
	v_pk_mul_f32 v[196:197], v[198:199], v[200:201]
	v_cvt_f32_ubyte2_e32 v0, v190
	v_pk_mul_f32 v[102:103], v[102:103], v[196:197]
	v_rcp_iflag_f32_e32 v196, v0
	v_cvt_f32_ubyte3_e32 v0, v190
	v_cvt_f32_ubyte1_e32 v201, v188
	v_cvt_f32_ubyte0_e32 v200, v188
	v_rcp_iflag_f32_e32 v197, v0
	v_pk_mul_f32 v[192:193], v[192:193], v[200:201]
	v_cvt_f32_ubyte0_e32 v0, v191
	v_pk_mul_f32 v[96:97], v[96:97], v[192:193]
	v_rcp_iflag_f32_e32 v192, v0
	v_cvt_f32_ubyte1_e32 v0, v191
	v_rcp_iflag_f32_e32 v193, v0
	v_cvt_f32_ubyte3_e32 v199, v188
	v_cvt_f32_ubyte2_e32 v198, v188
	v_cvt_f32_ubyte2_e32 v0, v191
	v_pk_mul_f32 v[196:197], v[196:197], v[198:199]
	v_rcp_iflag_f32_e32 v190, v0
	v_cvt_f32_ubyte3_e32 v0, v191
	v_cvt_f32_ubyte1_e32 v199, v189
	v_cvt_f32_ubyte0_e32 v198, v189
	v_pk_mul_f32 v[98:99], v[98:99], v[196:197]
	v_rcp_iflag_f32_e32 v191, v0
	v_cvt_f32_ubyte3_e32 v197, v189
	v_cvt_f32_ubyte2_e32 v196, v189
	v_pk_mul_f32 v[188:189], v[192:193], v[198:199]
	v_cvt_f32_ubyte0_e32 v0, v194
	v_pk_mul_f32 v[92:93], v[92:93], v[188:189]
	v_rcp_iflag_f32_e32 v188, v0
	v_cvt_f32_ubyte1_e32 v0, v194
	v_rcp_iflag_f32_e32 v189, v0
	v_pk_mul_f32 v[190:191], v[190:191], v[196:197]
	v_cvt_f32_ubyte2_e32 v0, v194
	v_pk_mul_f32 v[94:95], v[94:95], v[190:191]
	v_rcp_iflag_f32_e32 v190, v0
	v_cvt_f32_ubyte3_e32 v0, v194
	v_cvt_f32_ubyte1_e32 v197, v186
	v_cvt_f32_ubyte0_e32 v196, v186
	v_rcp_iflag_f32_e32 v191, v0
	v_pk_mul_f32 v[188:189], v[188:189], v[196:197]
	v_cvt_f32_ubyte0_e32 v0, v195
	v_pk_mul_f32 v[88:89], v[88:89], v[188:189]
	v_rcp_iflag_f32_e32 v188, v0
	v_cvt_f32_ubyte1_e32 v0, v195
	v_rcp_iflag_f32_e32 v189, v0
	v_cvt_f32_ubyte3_e32 v193, v186
	v_cvt_f32_ubyte2_e32 v192, v186
	v_pk_mul_f32 v[190:191], v[190:191], v[192:193]
	v_cvt_f32_ubyte2_e32 v0, v195
	v_pk_mul_f32 v[90:91], v[90:91], v[190:191]
	v_rcp_iflag_f32_e32 v190, v0
	v_cvt_f32_ubyte3_e32 v0, v195
	v_cvt_f32_ubyte1_e32 v195, v187
	v_cvt_f32_ubyte0_e32 v194, v187
	v_rcp_iflag_f32_e32 v191, v0
	v_cvt_f32_ubyte3_e32 v193, v187
	v_cvt_f32_ubyte2_e32 v192, v187
	v_pk_mul_f32 v[186:187], v[188:189], v[194:195]
	v_cvt_f32_ubyte0_e32 v0, v184
	v_pk_mul_f32 v[84:85], v[84:85], v[186:187]
	v_rcp_iflag_f32_e32 v186, v0
	v_cvt_f32_ubyte1_e32 v0, v184
	v_rcp_iflag_f32_e32 v187, v0
	v_pk_mul_f32 v[188:189], v[190:191], v[192:193]
	v_cvt_f32_ubyte2_e32 v0, v184
	v_pk_mul_f32 v[86:87], v[86:87], v[188:189]
	v_rcp_iflag_f32_e32 v188, v0
	v_cvt_f32_ubyte3_e32 v0, v184
	v_cvt_f32_ubyte1_e32 v193, v182
	v_cvt_f32_ubyte0_e32 v192, v182
	v_rcp_iflag_f32_e32 v189, v0
	v_pk_mul_f32 v[186:187], v[186:187], v[192:193]
	v_cvt_f32_ubyte0_e32 v0, v185
	v_pk_mul_f32 v[80:81], v[80:81], v[186:187]
	v_rcp_iflag_f32_e32 v186, v0
	v_cvt_f32_ubyte1_e32 v0, v185
	v_rcp_iflag_f32_e32 v187, v0
	v_cvt_f32_ubyte3_e32 v191, v182
	v_cvt_f32_ubyte2_e32 v190, v182
	v_cvt_f32_ubyte2_e32 v0, v185
	v_pk_mul_f32 v[188:189], v[188:189], v[190:191]
	v_rcp_iflag_f32_e32 v184, v0
	v_cvt_f32_ubyte3_e32 v0, v185
	v_cvt_f32_ubyte1_e32 v191, v183
	v_cvt_f32_ubyte0_e32 v190, v183
	v_pk_mul_f32 v[82:83], v[82:83], v[188:189]
	v_rcp_iflag_f32_e32 v185, v0
	v_cvt_f32_ubyte3_e32 v189, v183
	v_cvt_f32_ubyte2_e32 v188, v183
	v_pk_mul_f32 v[182:183], v[186:187], v[190:191]
	v_cvt_f32_ubyte0_e32 v0, v180
	v_pk_mul_f32 v[76:77], v[76:77], v[182:183]
	v_rcp_iflag_f32_e32 v182, v0
	v_cvt_f32_ubyte1_e32 v0, v180
	v_rcp_iflag_f32_e32 v183, v0
	v_pk_mul_f32 v[184:185], v[184:185], v[188:189]
	v_cvt_f32_ubyte2_e32 v0, v180
	v_pk_mul_f32 v[78:79], v[78:79], v[184:185]
	v_rcp_iflag_f32_e32 v184, v0
	v_cvt_f32_ubyte3_e32 v0, v180
	v_cvt_f32_ubyte1_e32 v189, v178
	v_cvt_f32_ubyte0_e32 v188, v178
	v_rcp_iflag_f32_e32 v185, v0
	v_pk_mul_f32 v[182:183], v[182:183], v[188:189]
	v_cvt_f32_ubyte0_e32 v0, v181
	v_pk_mul_f32 v[72:73], v[72:73], v[182:183]
	v_rcp_iflag_f32_e32 v182, v0
	v_cvt_f32_ubyte1_e32 v0, v181
	v_rcp_iflag_f32_e32 v183, v0
	v_cvt_f32_ubyte3_e32 v187, v178
	v_cvt_f32_ubyte2_e32 v186, v178
	v_cvt_f32_ubyte2_e32 v0, v181
	v_pk_mul_f32 v[184:185], v[184:185], v[186:187]
	v_rcp_iflag_f32_e32 v180, v0
	v_cvt_f32_ubyte3_e32 v0, v181
	v_cvt_f32_ubyte1_e32 v187, v179
	v_cvt_f32_ubyte0_e32 v186, v179
	v_pk_mul_f32 v[74:75], v[74:75], v[184:185]
	v_rcp_iflag_f32_e32 v181, v0
	v_cvt_f32_ubyte3_e32 v185, v179
	v_cvt_f32_ubyte2_e32 v184, v179
	v_pk_mul_f32 v[178:179], v[182:183], v[186:187]
; DI float rcpf_(float x) { return __builtin_amdgcn_rcpf(x); }
; DI float ub(unsigned w, int i) { return (float)((w >> (8 * i)) & 0xffu); }
;     DI void mid(f32x4 (&acc)[2][2][4][2], const pg8::Unit& u, int wr, int wc, int fr, int fq) const {
;     ...
; #pragma unroll
;                     for (int e = 0; e < 8; ++e)
;                         acc[ai][bj][m][e >> 2][e & 3] *= ub(g1[ai][m][bj][e >> 2], e & 3) * rcpf_(ub(g2[ai][m][bj][e >> 2], e & 3));
	v_cvt_f32_ubyte0_e32 v0, v176
	v_pk_mul_f32 v[68:69], v[68:69], v[178:179]
	v_rcp_iflag_f32_e32 v178, v0
	v_cvt_f32_ubyte1_e32 v0, v176
	v_rcp_iflag_f32_e32 v179, v0
	v_pk_mul_f32 v[180:181], v[180:181], v[184:185]
	v_cvt_f32_ubyte2_e32 v0, v176
	v_pk_mul_f32 v[70:71], v[70:71], v[180:181]
	v_rcp_iflag_f32_e32 v180, v0
	v_cvt_f32_ubyte3_e32 v0, v176
	v_cvt_f32_ubyte1_e32 v185, v174
	v_cvt_f32_ubyte0_e32 v184, v174
	v_rcp_iflag_f32_e32 v181, v0
	v_pk_mul_f32 v[178:179], v[178:179], v[184:185]
	v_cvt_f32_ubyte0_e32 v0, v177
	v_pk_mul_f32 v[64:65], v[64:65], v[178:179]
	v_rcp_iflag_f32_e32 v178, v0
	v_cvt_f32_ubyte1_e32 v0, v177
	v_rcp_iflag_f32_e32 v179, v0
	v_cvt_f32_ubyte3_e32 v183, v174
	v_cvt_f32_ubyte2_e32 v182, v174
	v_cvt_f32_ubyte2_e32 v0, v177
	v_pk_mul_f32 v[180:181], v[180:181], v[182:183]
	v_rcp_iflag_f32_e32 v176, v0
	v_cvt_f32_ubyte3_e32 v0, v177
	v_cvt_f32_ubyte1_e32 v183, v175
	v_cvt_f32_ubyte0_e32 v182, v175
	v_pk_mul_f32 v[66:67], v[66:67], v[180:181]
	v_rcp_iflag_f32_e32 v177, v0
	v_cvt_f32_ubyte3_e32 v181, v175
	v_cvt_f32_ubyte2_e32 v180, v175
	v_pk_mul_f32 v[174:175], v[178:179], v[182:183]
	v_cvt_f32_ubyte0_e32 v0, v170
	v_pk_mul_f32 v[60:61], v[60:61], v[174:175]
	v_rcp_iflag_f32_e32 v174, v0
	v_cvt_f32_ubyte1_e32 v0, v170
	v_rcp_iflag_f32_e32 v175, v0
	v_pk_mul_f32 v[176:177], v[176:177], v[180:181]
	v_cvt_f32_ubyte2_e32 v0, v170
	v_pk_mul_f32 v[62:63], v[62:63], v[176:177]
	v_rcp_iflag_f32_e32 v176, v0
	v_cvt_f32_ubyte3_e32 v0, v170
	v_cvt_f32_ubyte1_e32 v181, v172
	v_cvt_f32_ubyte0_e32 v180, v172
	v_rcp_iflag_f32_e32 v177, v0
	v_pk_mul_f32 v[174:175], v[174:175], v[180:181]
	v_cvt_f32_ubyte0_e32 v0, v171
	v_pk_mul_f32 v[56:57], v[56:57], v[174:175]
	v_rcp_iflag_f32_e32 v174, v0
	v_cvt_f32_ubyte1_e32 v0, v171
	v_rcp_iflag_f32_e32 v175, v0
	v_cvt_f32_ubyte2_e32 v0, v171
	v_rcp_iflag_f32_e32 v170, v0
	v_cvt_f32_ubyte3_e32 v0, v171
	v_rcp_iflag_f32_e32 v171, v0
	v_cvt_f32_ubyte3_e32 v179, v172
	v_cvt_f32_ubyte2_e32 v178, v172
	v_pk_mul_f32 v[176:177], v[176:177], v[178:179]
	v_cvt_f32_ubyte0_e32 v0, v168
	v_pk_mul_f32 v[58:59], v[58:59], v[176:177]
	v_cvt_f32_ubyte3_e32 v177, v173
	v_cvt_f32_ubyte2_e32 v176, v173
	v_pk_mul_f32 v[170:171], v[170:171], v[176:177]
	v_cvt_f32_ubyte1_e32 v179, v173
	v_pk_mul_f32 v[54:55], v[54:55], v[170:171]
	v_rcp_iflag_f32_e32 v170, v0
	v_cvt_f32_ubyte1_e32 v0, v168
	v_rcp_iflag_f32_e32 v171, v0
	v_cvt_f32_ubyte0_e32 v178, v173
	v_pk_mul_f32 v[172:173], v[174:175], v[178:179]
	v_cvt_f32_ubyte2_e32 v0, v168
	v_pk_mul_f32 v[52:53], v[52:53], v[172:173]
	v_rcp_iflag_f32_e32 v172, v0
	v_cvt_f32_ubyte3_e32 v0, v168
	v_cvt_f32_ubyte1_e32 v177, v166
	v_cvt_f32_ubyte0_e32 v176, v166
	v_rcp_iflag_f32_e32 v173, v0
	v_pk_mul_f32 v[170:171], v[170:171], v[176:177]
	v_cvt_f32_ubyte0_e32 v0, v169
	v_pk_mul_f32 v[48:49], v[48:49], v[170:171]
	v_rcp_iflag_f32_e32 v170, v0
	v_cvt_f32_ubyte1_e32 v0, v169
	v_rcp_iflag_f32_e32 v171, v0
	v_cvt_f32_ubyte3_e32 v175, v166
	v_cvt_f32_ubyte2_e32 v174, v166
	v_cvt_f32_ubyte2_e32 v0, v169
	v_pk_mul_f32 v[172:173], v[172:173], v[174:175]
	v_rcp_iflag_f32_e32 v168, v0
	v_cvt_f32_ubyte3_e32 v0, v169
	v_cvt_f32_ubyte1_e32 v175, v167
	v_cvt_f32_ubyte0_e32 v174, v167
	v_pk_mul_f32 v[50:51], v[50:51], v[172:173]
	v_rcp_iflag_f32_e32 v169, v0
	v_cvt_f32_ubyte3_e32 v173, v167
	v_cvt_f32_ubyte2_e32 v172, v167
	v_pk_mul_f32 v[166:167], v[170:171], v[174:175]
	v_cvt_f32_ubyte0_e32 v0, v164
	v_pk_mul_f32 v[44:45], v[44:45], v[166:167]
	v_rcp_iflag_f32_e32 v166, v0
	v_cvt_f32_ubyte1_e32 v0, v164
	v_rcp_iflag_f32_e32 v167, v0
	v_pk_mul_f32 v[168:169], v[168:169], v[172:173]
	v_cvt_f32_ubyte2_e32 v0, v164
	v_pk_mul_f32 v[46:47], v[46:47], v[168:169]
	v_rcp_iflag_f32_e32 v168, v0
	v_cvt_f32_ubyte3_e32 v0, v164
	v_cvt_f32_ubyte1_e32 v173, v162
	v_cvt_f32_ubyte0_e32 v172, v162
	v_rcp_iflag_f32_e32 v169, v0
	v_pk_mul_f32 v[166:167], v[166:167], v[172:173]
	v_cvt_f32_ubyte0_e32 v0, v165
	v_pk_mul_f32 v[40:41], v[40:41], v[166:167]
	v_rcp_iflag_f32_e32 v166, v0
	v_cvt_f32_ubyte1_e32 v0, v165
	v_rcp_iflag_f32_e32 v167, v0
	v_cvt_f32_ubyte3_e32 v171, v162
	v_cvt_f32_ubyte2_e32 v170, v162
	v_cvt_f32_ubyte2_e32 v0, v165
	v_pk_mul_f32 v[168:169], v[168:169], v[170:171]
	v_rcp_iflag_f32_e32 v164, v0
	v_cvt_f32_ubyte3_e32 v0, v165
	v_cvt_f32_ubyte1_e32 v171, v163
	v_cvt_f32_ubyte0_e32 v170, v163
	v_pk_mul_f32 v[42:43], v[42:43], v[168:169]
	v_rcp_iflag_f32_e32 v165, v0
	v_cvt_f32_ubyte3_e32 v169, v163
	v_cvt_f32_ubyte2_e32 v168, v163
	v_pk_mul_f32 v[162:163], v[166:167], v[170:171]
	v_cvt_f32_ubyte0_e32 v0, v160
	v_pk_mul_f32 v[36:37], v[36:37], v[162:163]
; DI float rcpf_(float x) { return __builtin_amdgcn_rcpf(x); }
; DI float ub(unsigned w, int i) { return (float)((w >> (8 * i)) & 0xffu); }
;     DI void mid(f32x4 (&acc)[2][2][4][2], const pg8::Unit& u, int wr, int wc, int fr, int fq) const {
;     ...
; #pragma unroll
;                     for (int e = 0; e < 8; ++e)
;                         acc[ai][bj][m][e >> 2][e & 3] *= ub(g1[ai][m][bj][e >> 2], e & 3) * rcpf_(ub(g2[ai][m][bj][e >> 2], e & 3));
	v_rcp_iflag_f32_e32 v162, v0
	v_cvt_f32_ubyte1_e32 v0, v160
	v_rcp_iflag_f32_e32 v163, v0
	v_pk_mul_f32 v[164:165], v[164:165], v[168:169]
	v_cvt_f32_ubyte2_e32 v0, v160
	v_pk_mul_f32 v[38:39], v[38:39], v[164:165]
	v_rcp_iflag_f32_e32 v164, v0
	v_cvt_f32_ubyte3_e32 v0, v160
	v_cvt_f32_ubyte1_e32 v169, v158
	v_cvt_f32_ubyte0_e32 v168, v158
	v_rcp_iflag_f32_e32 v165, v0
	v_pk_mul_f32 v[162:163], v[162:163], v[168:169]
	v_cvt_f32_ubyte0_e32 v0, v161
	v_pk_mul_f32 v[32:33], v[32:33], v[162:163]
	v_rcp_iflag_f32_e32 v162, v0
	v_cvt_f32_ubyte1_e32 v0, v161
	v_rcp_iflag_f32_e32 v163, v0
	v_cvt_f32_ubyte3_e32 v167, v158
	v_cvt_f32_ubyte2_e32 v166, v158
	v_cvt_f32_ubyte2_e32 v0, v161
	v_pk_mul_f32 v[164:165], v[164:165], v[166:167]
	v_rcp_iflag_f32_e32 v160, v0
	v_cvt_f32_ubyte3_e32 v0, v161
	v_cvt_f32_ubyte1_e32 v167, v159
	v_cvt_f32_ubyte0_e32 v166, v159
	v_pk_mul_f32 v[34:35], v[34:35], v[164:165]
	v_rcp_iflag_f32_e32 v161, v0
	v_cvt_f32_ubyte3_e32 v165, v159
	v_cvt_f32_ubyte2_e32 v164, v159
	v_pk_mul_f32 v[158:159], v[162:163], v[166:167]
	v_cvt_f32_ubyte0_e32 v0, v154
	v_pk_mul_f32 v[28:29], v[28:29], v[158:159]
	v_rcp_iflag_f32_e32 v158, v0
	v_cvt_f32_ubyte1_e32 v0, v154
	v_rcp_iflag_f32_e32 v159, v0
	v_pk_mul_f32 v[160:161], v[160:161], v[164:165]
	v_cvt_f32_ubyte2_e32 v0, v154
	v_pk_mul_f32 v[30:31], v[30:31], v[160:161]
	v_rcp_iflag_f32_e32 v160, v0
	v_cvt_f32_ubyte3_e32 v0, v154
	v_cvt_f32_ubyte1_e32 v165, v156
	v_cvt_f32_ubyte0_e32 v164, v156
	v_rcp_iflag_f32_e32 v161, v0
	v_pk_mul_f32 v[158:159], v[158:159], v[164:165]
	v_cvt_f32_ubyte0_e32 v0, v155
	v_pk_mul_f32 v[24:25], v[24:25], v[158:159]
	v_rcp_iflag_f32_e32 v158, v0
	v_cvt_f32_ubyte1_e32 v0, v155
	v_rcp_iflag_f32_e32 v159, v0
	v_cvt_f32_ubyte2_e32 v0, v155
	v_rcp_iflag_f32_e32 v154, v0
	v_cvt_f32_ubyte3_e32 v0, v155
	v_rcp_iflag_f32_e32 v155, v0
	v_cvt_f32_ubyte3_e32 v163, v156
	v_cvt_f32_ubyte2_e32 v162, v156
	v_pk_mul_f32 v[160:161], v[160:161], v[162:163]
	v_cvt_f32_ubyte0_e32 v0, v152
	v_pk_mul_f32 v[26:27], v[26:27], v[160:161]
	v_cvt_f32_ubyte3_e32 v161, v157
	v_cvt_f32_ubyte2_e32 v160, v157
	v_pk_mul_f32 v[154:155], v[154:155], v[160:161]
	v_cvt_f32_ubyte1_e32 v163, v157
	v_pk_mul_f32 v[22:23], v[22:23], v[154:155]
	v_rcp_iflag_f32_e32 v154, v0
	v_cvt_f32_ubyte1_e32 v0, v152
	v_rcp_iflag_f32_e32 v155, v0
	v_cvt_f32_ubyte0_e32 v162, v157
	v_pk_mul_f32 v[156:157], v[158:159], v[162:163]
	v_cvt_f32_ubyte2_e32 v0, v152
	v_pk_mul_f32 v[20:21], v[20:21], v[156:157]
	v_rcp_iflag_f32_e32 v156, v0
	v_cvt_f32_ubyte3_e32 v0, v152
	v_cvt_f32_ubyte1_e32 v161, v150
	v_cvt_f32_ubyte0_e32 v160, v150
	v_rcp_iflag_f32_e32 v157, v0
	v_pk_mul_f32 v[154:155], v[154:155], v[160:161]
	v_cvt_f32_ubyte0_e32 v0, v153
	v_pk_mul_f32 v[16:17], v[16:17], v[154:155]
	v_rcp_iflag_f32_e32 v154, v0
	v_cvt_f32_ubyte1_e32 v0, v153
	v_rcp_iflag_f32_e32 v155, v0
	v_cvt_f32_ubyte3_e32 v159, v150
	v_cvt_f32_ubyte2_e32 v158, v150
	v_cvt_f32_ubyte2_e32 v0, v153
	v_pk_mul_f32 v[156:157], v[156:157], v[158:159]
	v_rcp_iflag_f32_e32 v152, v0
	v_cvt_f32_ubyte3_e32 v0, v153
	v_cvt_f32_ubyte1_e32 v159, v151
	v_cvt_f32_ubyte0_e32 v158, v151
	v_pk_mul_f32 v[18:19], v[18:19], v[156:157]
	v_rcp_iflag_f32_e32 v153, v0
	v_cvt_f32_ubyte3_e32 v157, v151
	v_cvt_f32_ubyte2_e32 v156, v151
	v_pk_mul_f32 v[150:151], v[154:155], v[158:159]
	v_cvt_f32_ubyte0_e32 v0, v148
	v_pk_mul_f32 v[12:13], v[12:13], v[150:151]
	v_rcp_iflag_f32_e32 v150, v0
	v_cvt_f32_ubyte1_e32 v0, v148
	v_rcp_iflag_f32_e32 v151, v0
	v_pk_mul_f32 v[152:153], v[152:153], v[156:157]
	v_cvt_f32_ubyte2_e32 v0, v148
	v_pk_mul_f32 v[14:15], v[14:15], v[152:153]
	v_rcp_iflag_f32_e32 v152, v0
	v_cvt_f32_ubyte3_e32 v0, v148
	v_cvt_f32_ubyte1_e32 v157, v2
	v_cvt_f32_ubyte0_e32 v156, v2
	v_rcp_iflag_f32_e32 v153, v0
	v_pk_mul_f32 v[150:151], v[150:151], v[156:157]
	v_cvt_f32_ubyte0_e32 v0, v149
	v_pk_mul_f32 v[8:9], v[8:9], v[150:151]
	v_rcp_iflag_f32_e32 v150, v0
	v_cvt_f32_ubyte1_e32 v0, v149
	v_rcp_iflag_f32_e32 v151, v0
	v_cvt_f32_ubyte2_e32 v0, v149
	v_rcp_iflag_f32_e32 v148, v0
	v_cvt_f32_ubyte3_e32 v0, v149
	v_rcp_iflag_f32_e32 v149, v0
	v_cvt_f32_ubyte3_e32 v155, v2
	v_cvt_f32_ubyte2_e32 v154, v2
	v_pk_mul_f32 v[152:153], v[152:153], v[154:155]
	v_cvt_f32_ubyte1_e32 v155, v3
	v_pk_mul_f32 v[10:11], v[10:11], v[152:153]
	v_cvt_f32_ubyte3_e32 v153, v3
	v_cvt_f32_ubyte2_e32 v152, v3
	v_cvt_f32_ubyte0_e32 v154, v3
	v_pk_mul_f32 v[2:3], v[150:151], v[154:155]
	v_pk_mul_f32 v[148:149], v[148:149], v[152:153]
	v_pk_mul_f32 v[4:5], v[4:5], v[2:3]
	v_pk_mul_f32 v[6:7], v[6:7], v[148:149]
	s_branch .LBB0_448

; #define PG8_STAGE(bufoff, gbase, voff) do { _Pragma("unroll") for (int _i = 0; _i < 2; ++_i) \
;         __builtin_amdgcn_global_load_lds((const unsigned*)((const char*)(gbase) + (voff)[_i]), (LAS unsigned*)(lds + (bufoff) + ldsw + _i * 8192), 16, 0, 0); } while (0)
; #define PG8_LDA(dst, b, h) do { _Pragma("unroll") for (int m = 0; m < 4; ++m) _Pragma("unroll") for (int k = 0; k < 2; ++k) dst[m][k] = *(const LAS bf16x8*)(lds + PG8_SA(b, h) + aoff + m * 2048 + k * 1024); } while (0)
; #define PG8_LDB(dst, b, h) do { _Pragma("unroll") for (int n = 0; n < 2; ++n) _Pragma("unroll") for (int k = 0; k < 2; ++k) dst[n][k] = *(const LAS bf16x8*)(lds + PG8_SB(b, h) + boff + n * 2048 + k * 1024); } while (0)
; #define PG8_MMA(ai, bj, At, Bt) do { __builtin_amdgcn_s_setprio(1); _Pragma("unroll") for (int m = 0; m < 4; ++m) _Pragma("unroll") for (int n = 0; n < 2; ++n) _Pragma("unroll") for (int k = 0; k < 2; ++k) \
;         acc[ai][bj][m][n] = __builtin_amdgcn_mfma_f32_16x16x32_bf16(Bt[n][k], At[m][k], acc[ai][bj][m][n], 0, 0, 0); __builtin_amdgcn_s_setprio(0); } while (0)
; #define PG8_WAIT_L(n) asm volatile("s_waitcnt lgkmcnt(" #n ")" ::: "memory")
; #define PG8_BAR __builtin_amdgcn_s_barrier()
; #define PG8_SCHED __builtin_amdgcn_sched_barrier(0)
; template <class Epi>
; DI void gemm_phase(LAS unsigned char* lds, const Gemm g, const StaticOrder& S_, const Epi& E) {
;     ...
;         for (int t = tb; t < te; t += 2) {
;             const bool last = (t == nt - 2);
;             const bool hA = (t >= ksplit), hB = (t + 2 >= ksplit);
;             const char* a1 = (hA ? cA1 : cA0) + (size_t)(t + 1) * kstep;
;             const char* a2 = last ? nA0 : (hB ? cA1 : cA0) + (size_t)(t + 2) * kstep; const char* b2 = last ? nB0 : (hB ? cB1 : cB0) + (size_t)(t + 2) * kstep;
;             const char* a3 = a2 + kstep; const char* b3 = b2 + kstep;
;             PG8_LDB(B0, 0, 0); PG8_SCHED; PG8_LDA(At, 0, 0); PG8_STAGE(PG8_SA(1, 1), a1 + hstepA, voffA);
;             PG8_WAIT_L(8); PG8_BAR; PG8_WAIT_L(0); PG8_MMA(0, 0, At, B0); PG8_BAR; PG8_SCHED;
;             PG8_LDB(B1, 0, 1); PG8_STAGE(PG8_SB(0, 0), b2, voffB);
;             PG8_BAR; PG8_WAIT_L(0); PG8_MMA(0, 1, At, B1); PG8_BAR;
;             PG8_LDA(At, 0, 1); PG8_STAGE(PG8_SA(0, 0), a2, voffA);
;             PG8_BAR; PG8_WAIT_L(0); PG8_MMA(1, 0, At, B0); PG8_BAR; PG8_SCHED;
.LBB0_525:
	s_add_i32 s72, s46, 2
	s_cmp_gt_u32 s72, 29
	s_cselect_b64 s[48:49], -1, 0
	s_and_b64 vcc, s[48:49], exec
	s_cselect_b32 s48, s37, s40
	s_cselect_b32 s47, s39, s41
	s_cselect_b32 s49, s69, s43
	s_cselect_b32 s73, s68, s42
	s_add_u32 s48, s48, s44
	s_addc_u32 s47, s47, s45
	s_add_u32 s48, s48, 0xfff80080
	s_addc_u32 s47, s47, -1
	ds_read_b128 v[158:161], v153
	ds_read_b128 v[162:165], v153 offset:1024
	ds_read_b128 v[166:169], v153 offset:2048
	ds_read_b128 v[170:173], v153 offset:3072
	s_add_u32 s73, s73, s44
	s_addc_u32 s49, s49, s45
	s_add_u32 s73, s73, 0xfff80080
	s_addc_u32 s74, s49, -1
	s_cmp_eq_u32 s46, 28
	s_cselect_b32 s46, s71, s73
	s_cselect_b32 s49, s23, s47
	s_cselect_b32 s48, s70, s48
	s_cselect_b32 s47, s21, s74
	v_lshl_add_u64 v[208:209], v[146:147], 0, s[44:45]
	s_add_i32 m0, s54, 0xc000
	ds_read_b128 v[174:177], v154
	ds_read_b128 v[178:181], v154 offset:1024
	ds_read_b128 v[182:185], v154 offset:2048
	ds_read_b128 v[186:189], v154 offset:3072
	ds_read_b128 v[190:193], v154 offset:4096
	ds_read_b128 v[194:197], v154 offset:5120
	ds_read_b128 v[198:201], v154 offset:6144
	ds_read_b128 v[204:207], v154 offset:7168
	global_load_lds_dwordx4 v[208:209], off
	v_lshl_add_u64 v[208:209], v[148:149], 0, s[44:45]
	s_add_i32 m0, s54, 0xe000
	s_nop 0
	global_load_lds_dwordx4 v[208:209], off
	s_waitcnt lgkmcnt(8)
	s_setprio 1
	s_barrier
	s_waitcnt lgkmcnt(0)
	v_mfma_f32_16x16x32_bf16 v[124:127], v[158:161], v[174:177], v[124:127]
	v_mfma_f32_16x16x32_bf16 v[120:123], v[166:169], v[174:177], v[120:123]
	v_mfma_f32_16x16x32_bf16 v[108:111], v[158:161], v[182:185], v[108:111]
	v_mfma_f32_16x16x32_bf16 v[104:107], v[166:169], v[182:185], v[104:107]
	v_mfma_f32_16x16x32_bf16 v[92:95], v[158:161], v[190:193], v[92:95]
	v_mfma_f32_16x16x32_bf16 v[88:91], v[166:169], v[190:193], v[88:91]
	v_mfma_f32_16x16x32_bf16 v[76:79], v[158:161], v[198:201], v[76:79]
	v_mfma_f32_16x16x32_bf16 v[72:75], v[166:169], v[198:201], v[72:75]
	v_mfma_f32_16x16x32_bf16 v[124:127], v[162:165], v[178:181], v[124:127]
	v_mfma_f32_16x16x32_bf16 v[120:123], v[170:173], v[178:181], v[120:123]
	v_mfma_f32_16x16x32_bf16 v[108:111], v[162:165], v[186:189], v[108:111]
	v_mfma_f32_16x16x32_bf16 v[104:107], v[170:173], v[186:189], v[104:107]
	v_mfma_f32_16x16x32_bf16 v[92:95], v[162:165], v[194:197], v[92:95]
	v_mfma_f32_16x16x32_bf16 v[88:91], v[170:173], v[194:197], v[88:91]
	v_mfma_f32_16x16x32_bf16 v[76:79], v[162:165], v[204:207], v[76:79]
	v_mfma_f32_16x16x32_bf16 v[72:75], v[170:173], v[204:207], v[72:75]
	s_setprio 0
	s_barrier
	s_add_i32 s73, s66, s53
	v_lshl_add_u64 v[224:225], s[46:47], 0, v[130:131]
	s_mov_b32 m0, s73
	ds_read_b128 v[208:211], v155
	ds_read_b128 v[212:215], v155 offset:1024
	ds_read_b128 v[216:219], v155 offset:2048
	ds_read_b128 v[220:223], v155 offset:3072
	global_load_lds_dwordx4 v[224:225], off
	v_lshl_add_u64 v[226:227], s[46:47], 0, v[134:135]
	s_add_i32 m0, s73, 0x2000
	s_nop 0
	global_load_lds_dwordx4 v[226:227], off
	s_setprio 1
	s_barrier
	s_waitcnt lgkmcnt(0)
	v_mfma_f32_16x16x32_bf16 v[116:119], v[208:211], v[174:177], v[116:119]
	v_mfma_f32_16x16x32_bf16 v[112:115], v[216:219], v[174:177], v[112:115]
	v_mfma_f32_16x16x32_bf16 v[100:103], v[208:211], v[182:185], v[100:103]
	v_mfma_f32_16x16x32_bf16 v[96:99], v[216:219], v[182:185], v[96:99]
	v_mfma_f32_16x16x32_bf16 v[84:87], v[208:211], v[190:193], v[84:87]
	v_mfma_f32_16x16x32_bf16 v[80:83], v[216:219], v[190:193], v[80:83]
	v_mfma_f32_16x16x32_bf16 v[68:71], v[208:211], v[198:201], v[68:71]
	v_mfma_f32_16x16x32_bf16 v[64:67], v[216:219], v[198:201], v[64:67]
	v_mfma_f32_16x16x32_bf16 v[116:119], v[212:215], v[178:181], v[116:119]
	v_mfma_f32_16x16x32_bf16 v[112:115], v[220:223], v[178:181], v[112:115]
	v_mfma_f32_16x16x32_bf16 v[100:103], v[212:215], v[186:189], v[100:103]
	v_mfma_f32_16x16x32_bf16 v[96:99], v[220:223], v[186:189], v[96:99]
	v_mfma_f32_16x16x32_bf16 v[84:87], v[212:215], v[194:197], v[84:87]
	v_mfma_f32_16x16x32_bf16 v[80:83], v[220:223], v[194:197], v[80:83]
	v_mfma_f32_16x16x32_bf16 v[68:71], v[212:215], v[204:207], v[68:71]
	v_mfma_f32_16x16x32_bf16 v[64:67], v[220:223], v[204:207], v[64:67]
	s_setprio 0
	s_mov_b32 m0, s54
	v_lshl_add_u64 v[228:229], s[48:49], 0, v[128:129]
	s_barrier
	ds_read_b128 v[174:177], v154 offset:16384
	ds_read_b128 v[178:181], v154 offset:17408
	ds_read_b128 v[182:185], v154 offset:18432
	ds_read_b128 v[186:189], v154 offset:19456
	ds_read_b128 v[190:193], v154 offset:20480
	ds_read_b128 v[194:197], v154 offset:21504
	ds_read_b128 v[198:201], v154 offset:22528
	ds_read_b128 v[204:207], v154 offset:23552
	global_load_lds_dwordx4 v[228:229], off
	v_lshl_add_u64 v[230:231], s[48:49], 0, v[132:133]
	s_mov_b32 m0, s55
	s_nop 0
	global_load_lds_dwordx4 v[230:231], off
	s_setprio 1
	s_barrier
	s_waitcnt lgkmcnt(0)
	v_mfma_f32_16x16x32_bf16 v[60:63], v[158:161], v[174:177], v[60:63]
	v_mfma_f32_16x16x32_bf16 v[56:59], v[166:169], v[174:177], v[56:59]
	v_mfma_f32_16x16x32_bf16 v[44:47], v[158:161], v[182:185], v[44:47]
	v_mfma_f32_16x16x32_bf16 v[40:43], v[166:169], v[182:185], v[40:43]
	v_mfma_f32_16x16x32_bf16 v[28:31], v[158:161], v[190:193], v[28:31]
	v_mfma_f32_16x16x32_bf16 v[24:27], v[166:169], v[190:193], v[24:27]
	v_mfma_f32_16x16x32_bf16 v[12:15], v[158:161], v[198:201], v[12:15]
	v_mfma_f32_16x16x32_bf16 v[8:11], v[166:169], v[198:201], v[8:11]
	v_mfma_f32_16x16x32_bf16 v[60:63], v[162:165], v[178:181], v[60:63]
	v_mfma_f32_16x16x32_bf16 v[56:59], v[170:173], v[178:181], v[56:59]
	v_mfma_f32_16x16x32_bf16 v[44:47], v[162:165], v[186:189], v[44:47]
	v_mfma_f32_16x16x32_bf16 v[40:43], v[170:173], v[186:189], v[40:43]
	v_mfma_f32_16x16x32_bf16 v[28:31], v[162:165], v[194:197], v[28:31]
	v_mfma_f32_16x16x32_bf16 v[24:27], v[170:173], v[194:197], v[24:27]
	v_mfma_f32_16x16x32_bf16 v[12:15], v[162:165], v[204:207], v[12:15]
	v_mfma_f32_16x16x32_bf16 v[8:11], v[170:173], v[204:207], v[8:11]
	s_setprio 0
	s_barrier
; #define PG8_STAGE(bufoff, gbase, voff) do { _Pragma("unroll") for (int _i = 0; _i < 2; ++_i) \
;         __builtin_amdgcn_global_load_lds((const unsigned*)((const char*)(gbase) + (voff)[_i]), (LAS unsigned*)(lds + (bufoff) + ldsw + _i * 8192), 16, 0, 0); } while (0)
; #define PG8_LDA(dst, b, h) do { _Pragma("unroll") for (int m = 0; m < 4; ++m) _Pragma("unroll") for (int k = 0; k < 2; ++k) dst[m][k] = *(const LAS bf16x8*)(lds + PG8_SA(b, h) + aoff + m * 2048 + k * 1024); } while (0)
; #define PG8_LDB(dst, b, h) do { _Pragma("unroll") for (int n = 0; n < 2; ++n) _Pragma("unroll") for (int k = 0; k < 2; ++k) dst[n][k] = *(const LAS bf16x8*)(lds + PG8_SB(b, h) + boff + n * 2048 + k * 1024); } while (0)
; #define PG8_MMA(ai, bj, At, Bt) do { __builtin_amdgcn_s_setprio(1); _Pragma("unroll") for (int m = 0; m < 4; ++m) _Pragma("unroll") for (int n = 0; n < 2; ++n) _Pragma("unroll") for (int k = 0; k < 2; ++k) \
;         acc[ai][bj][m][n] = __builtin_amdgcn_mfma_f32_16x16x32_bf16(Bt[n][k], At[m][k], acc[ai][bj][m][n], 0, 0, 0); __builtin_amdgcn_s_setprio(0); } while (0)
; #define PG8_WAIT_V(n) asm volatile("s_waitcnt vmcnt(" #n ")" ::: "memory")
; #define PG8_WAIT_L(n) asm volatile("s_waitcnt lgkmcnt(" #n ")" ::: "memory")
; #define PG8_BAR __builtin_amdgcn_s_barrier()
; #define PG8_SCHED __builtin_amdgcn_sched_barrier(0)
; template <class Epi>
; DI void gemm_phase(LAS unsigned char* lds, const Gemm g, const StaticOrder& S_, const Epi& E) {
;     ...
;             PG8_STAGE(PG8_SB(0, 1), b2 + hstepB, voffB);
;             PG8_WAIT_V(6); PG8_BAR; PG8_MMA(1, 1, At, B1); PG8_BAR;
;             PG8_LDB(B0, 1, 0); PG8_SCHED; PG8_LDA(At, 1, 0); PG8_STAGE(PG8_SA(0, 1), a2 + hstepA, voffA);
;             PG8_WAIT_L(8); PG8_BAR; PG8_WAIT_L(0); PG8_MMA(0, 0, At, B0); PG8_BAR; PG8_SCHED;
;             PG8_LDB(B1, 1, 1); PG8_STAGE(PG8_SB(1, 0), b3, voffB);
;             PG8_BAR; PG8_WAIT_L(0); PG8_MMA(0, 1, At, B1); PG8_BAR;
	s_add_u32 s74, s46, 0x80000
	s_addc_u32 s75, s47, 0
	s_add_i32 s73, s67, s53
	v_lshl_add_u64 v[158:159], s[74:75], 0, v[130:131]
	s_mov_b32 m0, s73
	s_nop 0
	global_load_lds_dwordx4 v[158:159], off
	v_lshl_add_u64 v[158:159], s[74:75], 0, v[134:135]
	s_add_i32 m0, s73, 0x2000
	s_nop 0
	global_load_lds_dwordx4 v[158:159], off
	s_waitcnt vmcnt(6)
	s_setprio 1
	s_barrier
	v_mfma_f32_16x16x32_bf16 v[52:55], v[208:211], v[174:177], v[52:55]
	v_mfma_f32_16x16x32_bf16 v[48:51], v[216:219], v[174:177], v[48:51]
	v_mfma_f32_16x16x32_bf16 v[36:39], v[208:211], v[182:185], v[36:39]
	v_mfma_f32_16x16x32_bf16 v[32:35], v[216:219], v[182:185], v[32:35]
	v_mfma_f32_16x16x32_bf16 v[20:23], v[208:211], v[190:193], v[20:23]
	v_mfma_f32_16x16x32_bf16 v[16:19], v[216:219], v[190:193], v[16:19]
	v_mfma_f32_16x16x32_bf16 v[4:7], v[208:211], v[198:201], v[4:7]
	v_mfma_f32_16x16x32_bf16 v[0:3], v[216:219], v[198:201], v[0:3]
	v_mfma_f32_16x16x32_bf16 v[52:55], v[212:215], v[178:181], v[52:55]
	v_mfma_f32_16x16x32_bf16 v[48:51], v[220:223], v[178:181], v[48:51]
	v_mfma_f32_16x16x32_bf16 v[36:39], v[212:215], v[186:189], v[36:39]
	v_mfma_f32_16x16x32_bf16 v[32:35], v[220:223], v[186:189], v[32:35]
	v_mfma_f32_16x16x32_bf16 v[20:23], v[212:215], v[194:197], v[20:23]
	v_mfma_f32_16x16x32_bf16 v[16:19], v[220:223], v[194:197], v[16:19]
	v_mfma_f32_16x16x32_bf16 v[4:7], v[212:215], v[204:207], v[4:7]
	v_mfma_f32_16x16x32_bf16 v[0:3], v[220:223], v[204:207], v[0:3]
	s_setprio 0
	s_add_i32 s73, 0, 0x18000
	v_add_u32_e32 v136, s73, v151
	s_barrier
	ds_read_b128 v[158:161], v136
	ds_read_b128 v[162:165], v136 offset:1024
	ds_read_b128 v[166:169], v136 offset:2048
	ds_read_b128 v[170:173], v136 offset:3072
	s_add_u32 s48, s48, 0x80000
	s_addc_u32 s49, s49, 0
	s_mov_b32 m0, s56
	v_lshl_add_u64 v[208:209], s[48:49], 0, v[128:129]
	ds_read_b128 v[174:177], v154 offset:32768
	ds_read_b128 v[178:181], v154 offset:33792
	ds_read_b128 v[182:185], v154 offset:34816
	ds_read_b128 v[186:189], v154 offset:35840
	ds_read_b128 v[190:193], v154 offset:36864
	ds_read_b128 v[194:197], v154 offset:37888
	ds_read_b128 v[198:201], v154 offset:38912
	ds_read_b128 v[204:207], v154 offset:39936
	global_load_lds_dwordx4 v[208:209], off
	v_lshl_add_u64 v[208:209], s[48:49], 0, v[132:133]
	s_mov_b32 m0, s57
	s_nop 0
	global_load_lds_dwordx4 v[208:209], off
	s_waitcnt lgkmcnt(8)
	s_setprio 1
	s_barrier
	s_waitcnt lgkmcnt(0)
	v_mfma_f32_16x16x32_bf16 v[124:127], v[158:161], v[174:177], v[124:127]
	v_mfma_f32_16x16x32_bf16 v[120:123], v[166:169], v[174:177], v[120:123]
	v_mfma_f32_16x16x32_bf16 v[108:111], v[158:161], v[182:185], v[108:111]
	v_mfma_f32_16x16x32_bf16 v[104:107], v[166:169], v[182:185], v[104:107]
	v_mfma_f32_16x16x32_bf16 v[92:95], v[158:161], v[190:193], v[92:95]
	v_mfma_f32_16x16x32_bf16 v[88:91], v[166:169], v[190:193], v[88:91]
	v_mfma_f32_16x16x32_bf16 v[76:79], v[158:161], v[198:201], v[76:79]
	v_mfma_f32_16x16x32_bf16 v[72:75], v[166:169], v[198:201], v[72:75]
	v_mfma_f32_16x16x32_bf16 v[124:127], v[162:165], v[178:181], v[124:127]
	v_mfma_f32_16x16x32_bf16 v[120:123], v[170:173], v[178:181], v[120:123]
	v_mfma_f32_16x16x32_bf16 v[108:111], v[162:165], v[186:189], v[108:111]
	v_mfma_f32_16x16x32_bf16 v[104:107], v[170:173], v[186:189], v[104:107]
	v_mfma_f32_16x16x32_bf16 v[92:95], v[162:165], v[194:197], v[92:95]
	v_mfma_f32_16x16x32_bf16 v[88:91], v[170:173], v[194:197], v[88:91]
	v_mfma_f32_16x16x32_bf16 v[76:79], v[162:165], v[204:207], v[76:79]
	v_mfma_f32_16x16x32_bf16 v[72:75], v[170:173], v[204:207], v[72:75]
	s_setprio 0
	s_barrier
	s_add_i32 s48, 0, 0x1c000
	s_add_i32 s49, s73, s53
	v_add_u32_e32 v136, s48, v151
	v_lshl_add_u64 v[224:225], v[224:225], 0, s[16:17]
	s_mov_b32 m0, s49
	ds_read_b128 v[208:211], v136
	ds_read_b128 v[212:215], v136 offset:1024
	ds_read_b128 v[216:219], v136 offset:2048
	ds_read_b128 v[220:223], v136 offset:3072
	global_load_lds_dwordx4 v[224:225], off
	v_lshl_add_u64 v[224:225], v[226:227], 0, s[16:17]
	s_add_i32 m0, s49, 0x2000
	s_nop 0
	global_load_lds_dwordx4 v[224:225], off
	s_setprio 1
	s_barrier
	s_waitcnt lgkmcnt(0)
	v_mfma_f32_16x16x32_bf16 v[116:119], v[208:211], v[174:177], v[116:119]
	v_mfma_f32_16x16x32_bf16 v[112:115], v[216:219], v[174:177], v[112:115]
	v_mfma_f32_16x16x32_bf16 v[100:103], v[208:211], v[182:185], v[100:103]
	v_mfma_f32_16x16x32_bf16 v[96:99], v[216:219], v[182:185], v[96:99]
	v_mfma_f32_16x16x32_bf16 v[84:87], v[208:211], v[190:193], v[84:87]
	v_mfma_f32_16x16x32_bf16 v[80:83], v[216:219], v[190:193], v[80:83]
	v_mfma_f32_16x16x32_bf16 v[68:71], v[208:211], v[198:201], v[68:71]
	v_mfma_f32_16x16x32_bf16 v[64:67], v[216:219], v[198:201], v[64:67]
	v_mfma_f32_16x16x32_bf16 v[116:119], v[212:215], v[178:181], v[116:119]
	v_mfma_f32_16x16x32_bf16 v[112:115], v[220:223], v[178:181], v[112:115]
	v_mfma_f32_16x16x32_bf16 v[100:103], v[212:215], v[186:189], v[100:103]
	v_mfma_f32_16x16x32_bf16 v[96:99], v[220:223], v[186:189], v[96:99]
	v_mfma_f32_16x16x32_bf16 v[84:87], v[212:215], v[194:197], v[84:87]
	v_mfma_f32_16x16x32_bf16 v[80:83], v[220:223], v[194:197], v[80:83]
	v_mfma_f32_16x16x32_bf16 v[68:71], v[212:215], v[204:207], v[68:71]
	v_mfma_f32_16x16x32_bf16 v[64:67], v[220:223], v[204:207], v[64:67]
	s_setprio 0
	s_mov_b32 m0, s59
	v_lshl_add_u64 v[224:225], v[228:229], 0, s[16:17]
	s_barrier
; DI unsigned cvtpk(float lo, float hi) { unsigned r; asm volatile("v_cvt_pk_bf16_f32 %0, %1, %2" : "=v"(r) : "v"(lo), "v"(hi)); return r; }
; #define PG8_STAGE(bufoff, gbase, voff) do { _Pragma("unroll") for (int _i = 0; _i < 2; ++_i) \
;         __builtin_amdgcn_global_load_lds((const unsigned*)((const char*)(gbase) + (voff)[_i]), (LAS unsigned*)(lds + (bufoff) + ldsw + _i * 8192), 16, 0, 0); } while (0)
; #define PG8_LDA(dst, b, h) do { _Pragma("unroll") for (int m = 0; m < 4; ++m) _Pragma("unroll") for (int k = 0; k < 2; ++k) dst[m][k] = *(const LAS bf16x8*)(lds + PG8_SA(b, h) + aoff + m * 2048 + k * 1024); } while (0)
; #define PG8_WAIT_V(n) asm volatile("s_waitcnt vmcnt(" #n ")" ::: "memory")
; #define PG8_WAIT_L(n) asm volatile("s_waitcnt lgkmcnt(" #n ")" ::: "memory")
; #define PG8_BAR __builtin_amdgcn_s_barrier()
; #define PG8_SCHED __builtin_amdgcn_sched_barrier(0)
; template <class Epi>
; DI void gemm_phase(LAS unsigned char* lds, const Gemm g, const StaticOrder& S_, const Epi& E) {
;     ...
;             PG8_BAR; PG8_WAIT_L(0); PG8_MMA(0, 1, At, B1); PG8_BAR;
;             PG8_LDA(At, 1, 1); PG8_STAGE(PG8_SA(1, 0), a3, voffA);
;             PG8_BAR; PG8_WAIT_L(0); PG8_MMA(1, 0, At, B0); PG8_BAR; PG8_SCHED;
;             PG8_STAGE(PG8_SB(1, 1), b3 + hstepB, voffB);
;             PG8_WAIT_V(6); PG8_BAR; PG8_MMA(1, 1, At, B1); PG8_BAR;
;     DI void operator()(const f32x4 (&acc)[2][2][4][2], const pg8::Unit& u, int wr, int wc, int fr, int fq) const {
;     ...
;         for (int ai = 0; ai < 2; ++ai)
; #pragma unroll
;             for (int m = 0; m < 4; ++m) {
;                 const unsigned row = r0_ + ai * 128 + m * 16; float s = 0.f;
; #pragma unroll
;                 for (int bj = 0; bj < 2; ++bj) {
;                     const f32x4 v0 = acc[ai][bj][m][0], v1 = acc[ai][bj][m][1];
;                     s += v0[0] * v0[0] + v0[1] * v0[1] + v0[2] * v0[2] + v0[3] * v0[3] + v1[0] * v1[0] + v1[1] * v1[1] + v1[2] * v1[2] + v1[3] * v1[3];
;                     u32x4 w = {cvtpk(v0[0], v0[1]), cvtpk(v0[2], v0[3]), cvtpk(v1[0], v1[1]), cvtpk(v1[2], v1[3])};
;                     stg128(o2, row * 4096u + c0_ + bj * 256u, w);
;                 }
;                 s += __shfl_xor(s, 16); s += __shfl_xor(s, 32);
;                 if (fq == 0) ssq[(size_t)row * 32 + u.pn * 4 + wc] = s;
	ds_read_b128 v[174:177], v154 offset:49152
	ds_read_b128 v[178:181], v154 offset:50176
	ds_read_b128 v[182:185], v154 offset:51200
	ds_read_b128 v[186:189], v154 offset:52224
	ds_read_b128 v[190:193], v154 offset:53248
	ds_read_b128 v[194:197], v154 offset:54272
	ds_read_b128 v[198:201], v154 offset:55296
	ds_read_b128 v[204:207], v154 offset:56320
	global_load_lds_dwordx4 v[224:225], off
	v_lshl_add_u64 v[224:225], v[230:231], 0, s[16:17]
	s_mov_b32 m0, s60
	s_nop 0
	global_load_lds_dwordx4 v[224:225], off
	s_setprio 1
	s_barrier
	s_waitcnt lgkmcnt(0)
	v_mfma_f32_16x16x32_bf16 v[60:63], v[158:161], v[174:177], v[60:63]
	v_mfma_f32_16x16x32_bf16 v[56:59], v[166:169], v[174:177], v[56:59]
	v_mfma_f32_16x16x32_bf16 v[44:47], v[158:161], v[182:185], v[44:47]
	v_mfma_f32_16x16x32_bf16 v[40:43], v[166:169], v[182:185], v[40:43]
	v_mfma_f32_16x16x32_bf16 v[28:31], v[158:161], v[190:193], v[28:31]
	v_mfma_f32_16x16x32_bf16 v[24:27], v[166:169], v[190:193], v[24:27]
	v_mfma_f32_16x16x32_bf16 v[12:15], v[158:161], v[198:201], v[12:15]
	v_mfma_f32_16x16x32_bf16 v[8:11], v[166:169], v[198:201], v[8:11]
	v_mfma_f32_16x16x32_bf16 v[60:63], v[162:165], v[178:181], v[60:63]
	v_mfma_f32_16x16x32_bf16 v[56:59], v[170:173], v[178:181], v[56:59]
	v_mfma_f32_16x16x32_bf16 v[44:47], v[162:165], v[186:189], v[44:47]
	v_mfma_f32_16x16x32_bf16 v[40:43], v[170:173], v[186:189], v[40:43]
	v_mfma_f32_16x16x32_bf16 v[28:31], v[162:165], v[194:197], v[28:31]
	v_mfma_f32_16x16x32_bf16 v[24:27], v[170:173], v[194:197], v[24:27]
	v_mfma_f32_16x16x32_bf16 v[12:15], v[162:165], v[204:207], v[12:15]
	v_mfma_f32_16x16x32_bf16 v[8:11], v[170:173], v[204:207], v[8:11]
	s_setprio 0
	s_barrier
	s_add_u32 s46, s46, 0x80080
	s_addc_u32 s47, s47, 0
	s_add_i32 s48, s48, s53
	v_lshl_add_u64 v[158:159], s[46:47], 0, v[130:131]
	s_mov_b32 m0, s48
	s_nop 0
	global_load_lds_dwordx4 v[158:159], off
	v_lshl_add_u64 v[158:159], s[46:47], 0, v[134:135]
	s_add_i32 m0, s48, 0x2000
	s_nop 0
	global_load_lds_dwordx4 v[158:159], off
	s_waitcnt vmcnt(6)
	s_setprio 1
	s_barrier
	v_mfma_f32_16x16x32_bf16 v[52:55], v[208:211], v[174:177], v[52:55]
	v_mfma_f32_16x16x32_bf16 v[48:51], v[216:219], v[174:177], v[48:51]
	v_mfma_f32_16x16x32_bf16 v[36:39], v[208:211], v[182:185], v[36:39]
	v_mfma_f32_16x16x32_bf16 v[32:35], v[216:219], v[182:185], v[32:35]
	v_mfma_f32_16x16x32_bf16 v[20:23], v[208:211], v[190:193], v[20:23]
	v_mfma_f32_16x16x32_bf16 v[16:19], v[216:219], v[190:193], v[16:19]
	v_mfma_f32_16x16x32_bf16 v[4:7], v[208:211], v[198:201], v[4:7]
	v_mfma_f32_16x16x32_bf16 v[0:3], v[216:219], v[198:201], v[0:3]
	v_mfma_f32_16x16x32_bf16 v[52:55], v[212:215], v[178:181], v[52:55]
	v_mfma_f32_16x16x32_bf16 v[48:51], v[220:223], v[178:181], v[48:51]
	v_mfma_f32_16x16x32_bf16 v[36:39], v[212:215], v[186:189], v[36:39]
	v_mfma_f32_16x16x32_bf16 v[32:35], v[220:223], v[186:189], v[32:35]
	v_mfma_f32_16x16x32_bf16 v[20:23], v[212:215], v[194:197], v[20:23]
	v_mfma_f32_16x16x32_bf16 v[16:19], v[220:223], v[194:197], v[16:19]
	v_mfma_f32_16x16x32_bf16 v[4:7], v[212:215], v[204:207], v[4:7]
	v_mfma_f32_16x16x32_bf16 v[0:3], v[220:223], v[204:207], v[0:3]
	s_setprio 0
	s_add_u32 s44, s44, 0x100
	s_addc_u32 s45, s45, 0
	s_mov_b32 s46, s72
	s_barrier
	s_cbranch_vccz .LBB0_525
	v_mul_f32_e32 v148, v125, v125
	v_fmac_f32_e32 v148, v124, v124
	v_fmac_f32_e32 v148, v126, v126
	v_fmac_f32_e32 v148, v127, v127
	v_fmac_f32_e32 v148, v120, v120
	v_cvt_pk_bf16_f32 v124, v124, v125
	v_cvt_pk_bf16_f32 v125, v126, v127
	v_cvt_pk_bf16_f32 v126, v120, v121
	v_mul_f32_e32 v120, v117, v117
	v_fmac_f32_e32 v120, v116, v116
	v_fmac_f32_e32 v120, v118, v118
	v_fmac_f32_e32 v120, v119, v119
	v_fmac_f32_e32 v120, v112, v112
	v_fmac_f32_e32 v148, v121, v121
	v_fmac_f32_e32 v120, v113, v113
	v_fmac_f32_e32 v148, v122, v122
	v_fmac_f32_e32 v120, v114, v114
	v_fmac_f32_e32 v148, v123, v123
	v_fmac_f32_e32 v120, v115, v115
	v_and_b32_e32 v127, 64, v156
	v_add_f32_e32 v121, v148, v120
	v_xor_b32_e32 v120, 16, v156
	v_add_u32_e32 v148, 64, v127
	v_cmp_lt_i32_e32 vcc, v120, v148
	v_lshl_add_u32 v136, s38, 8, v150
	v_lshl_or_b32 v146, s36, 9, v152
	v_cndmask_b32_e32 v120, v156, v120, vcc
	v_lshlrev_b32_e32 v120, 2, v120
	ds_bpermute_b32 v149, v120, v121
	v_lshl_add_u32 v147, v136, 12, v146
	v_cvt_pk_bf16_f32 v127, v122, v123
	global_store_dwordx4 v147, v[124:127], s[18:19]
	v_cvt_pk_bf16_f32 v122, v116, v117
	v_xor_b32_e32 v116, 32, v156
	v_cmp_lt_i32_e32 vcc, v116, v148
	s_waitcnt lgkmcnt(0)
	v_add_f32_e32 v117, v121, v149
	s_lshl_b32 s36, s36, 2
	v_cndmask_b32_e32 v116, v156, v116, vcc
	v_lshlrev_b32_e32 v116, 2, v116
	v_cvt_pk_bf16_f32 v123, v118, v119
	ds_bpermute_b32 v118, v116, v117
	s_ashr_i32 s37, s36, 31
	s_lshl_b64 s[36:37], s[36:37], 2
	s_add_u32 s36, s61, s36
	s_addc_u32 s37, s62, s37
	v_cvt_pk_bf16_f32 v124, v112, v113
	v_or_b32_e32 v112, 0x100, v147
	v_cvt_pk_bf16_f32 v125, v114, v115
	global_store_dwordx4 v112, v[122:125], s[18:19]
	s_and_saveexec_b64 s[38:39], s[6:7]
	s_cbranch_execz .LBB0_528
	v_lshlrev_b64 v[112:113], 7, v[136:137]
	v_lshl_add_u64 v[112:113], s[36:37], 0, v[112:113]
	s_waitcnt lgkmcnt(0)
	v_add_f32_e32 v114, v117, v118
	global_store_dword v[112:113], v114, off
